# all six K-loops: the s_barrier ending each 32-MFMA segment moved 2 MFMAs earlier (priority drop stays after the last MFMA)
# speedup vs baseline: 1.1194x; 1.1194x over previous
; #define PG8_STAGE(bufoff, gbase, voff) do { _Pragma("unroll") for (int _i = 0; _i < 2; ++_i) \
;         __builtin_amdgcn_global_load_lds((const unsigned*)((const char*)(gbase) + (voff)[_i]), (PG8_LAS unsigned*)(lds + (bufoff) + ldsw + _i * 8192), 16, 0, 0); } while (0)
; #define PG8_LDA(dst, b, h) do { _Pragma("unroll") for (int m = 0; m < 4; ++m) _Pragma("unroll") for (int k = 0; k < 2; ++k) dst[m][k] = *(const PG8_LAS bf16x8*)(lds + PG8_SA(b, h) + aoff + m * 2048 + k * 1024); } while (0)
; #define PG8_LDB(dst, b, h) do { _Pragma("unroll") for (int n = 0; n < 2; ++n) _Pragma("unroll") for (int k = 0; k < 2; ++k) dst[n][k] = *(const PG8_LAS bf16x8*)(lds + PG8_SB(b, h) + boff + n * 2048 + k * 1024); } while (0)
; #define PG8_MMA(ai, bj, At, Bt) do { __builtin_amdgcn_s_setprio(1); _Pragma("unroll") for (int m = 0; m < 4; ++m) _Pragma("unroll") for (int n = 0; n < 2; ++n) _Pragma("unroll") for (int k = 0; k < 2; ++k) \
;         acc[ai][bj][m][n] = __builtin_amdgcn_mfma_f32_16x16x32_bf16(Bt[n][k], At[m][k], acc[ai][bj][m][n], 0, 0, 0); __builtin_amdgcn_s_setprio(0); } while (0)
; #define PG8_WAIT_V(n) asm volatile("s_waitcnt vmcnt(" #n ")" ::: "memory")
; #define PG8_WAIT_L(n) asm volatile("s_waitcnt lgkmcnt(" #n ")" ::: "memory")
; #define PG8_BAR __builtin_amdgcn_s_barrier()
; #define PG8_SCHED __builtin_amdgcn_sched_barrier(0)
; template <class Epi, class Sched, bool ALIGN_EPI = false, bool SP2 = false>
; __device__ __forceinline__ void gemm_phase(PG8_LAS unsigned char* lds, const Gemm g, const Sched& S, const Epi& E) {
;     ...
;             const bool last = (t == nt - 2);
;             const char* a1 = cA + (size_t)(t + 1) * kstep;
;             const char* a2 = last ? nA : cA + (size_t)(t + 2) * kstep; const char* b2 = last ? nB : cB + (size_t)(t + 2) * kstep;
;             const char* a3 = a2 + kstep; const char* b3 = b2 + kstep;
;             if (last && has_next) S.a_ready(nxt);
;             if constexpr (SP2) {
;             PG8_LDB(B0, 0, 0); PG8_LDB(B1, 0, 1); PG8_SCHED; PG8_LDA(At, 0, 0); PG8_STAGE(PG8_SA(1, 1), a1 + hstep, voffA);
;             PG8_WAIT_V(8); PG8_WAIT_L(0); PG8_BAR; PG8_MMA(0, 0, At, B0); PG8_MMA(0, 1, At, B1); PG8_BAR; PG8_SCHED;
;             PG8_LDA(At, 0, 1); PG8_STAGE(PG8_SB(0, 0), b2, voffB); PG8_STAGE(PG8_SB(0, 1), b2 + hstep, voffB); PG8_STAGE(PG8_SA(0, 0), a2, voffA);
.LBB0_327:
	v_or_b32_e32 v68, 0x10000, v180
	v_add_u32_e32 v72, 0x10400, v180
	v_add_u32_e32 v76, 0x10800, v180
	v_add_u32_e32 v80, 0x10c00, v180
	v_or_b32_e32 v174, 0x14000, v180
	v_add_u32_e32 v181, 0x14400, v180
	ds_read_b128 v[68:71], v68
	ds_read_b128 v[72:75], v72
	ds_read_b128 v[76:79], v76
	ds_read_b128 v[80:83], v80
	ds_read_b128 v[174:177], v174
	ds_read_b128 v[182:185], v181
	v_add_u32_e32 v181, 0x14800, v180
	v_add_u32_e32 v190, 0x14c00, v180
	ds_read_b128 v[186:189], v181
	ds_read_b128 v[210:213], v190
	s_add_u32 s2, s0, 0xfffc0080
	s_addc_u32 s3, s1, -1
	s_cmp_eq_u32 s56, 12
	s_cselect_b32 s5, s27, s3
	s_cselect_b32 s4, s52, s2
	s_cselect_b32 s3, s25, s55
	s_cselect_b32 s2, s53, s54
	v_lshl_add_u64 v[190:191], s[0:1], 0, v[170:171]
	s_add_i32 m0, s29, 0xc000
	ds_read_b128 v[214:217], v179
	ds_read_b128 v[218:221], v179 offset:1024
	ds_read_b128 v[222:225], v179 offset:2048
	ds_read_b128 v[226:229], v179 offset:3072
	ds_read_b128 v[230:233], v179 offset:4096
	ds_read_b128 v[234:237], v179 offset:5120
	ds_read_b128 v[238:241], v179 offset:6144
	ds_read_b128 v[242:245], v179 offset:7168
	global_load_lds_dwordx4 v[190:191], off
	v_lshl_add_u64 v[190:191], s[0:1], 0, v[172:173]
	s_add_i32 m0, s29, 0xe000
	s_nop 0
	global_load_lds_dwordx4 v[190:191], off
	s_waitcnt vmcnt(8)
	s_waitcnt lgkmcnt(0)
	s_barrier
	s_setprio 1
	s_waitcnt lgkmcnt(0)
	v_mfma_f32_16x16x32_bf16 v[140:143], v[68:71], v[214:217], v[140:143]
	v_mfma_f32_16x16x32_bf16 v[136:139], v[76:79], v[214:217], v[136:139]
	v_mfma_f32_16x16x32_bf16 v[124:127], v[68:71], v[222:225], v[124:127]
	v_mfma_f32_16x16x32_bf16 v[120:123], v[76:79], v[222:225], v[120:123]
	v_mfma_f32_16x16x32_bf16 v[108:111], v[68:71], v[230:233], v[108:111]
	v_mfma_f32_16x16x32_bf16 v[104:107], v[76:79], v[230:233], v[104:107]
	v_mfma_f32_16x16x32_bf16 v[92:95], v[68:71], v[238:241], v[92:95]
	v_mfma_f32_16x16x32_bf16 v[88:91], v[76:79], v[238:241], v[88:91]
	v_mfma_f32_16x16x32_bf16 v[140:143], v[72:75], v[218:221], v[140:143]
	v_mfma_f32_16x16x32_bf16 v[136:139], v[80:83], v[218:221], v[136:139]
	v_mfma_f32_16x16x32_bf16 v[124:127], v[72:75], v[226:229], v[124:127]
	v_mfma_f32_16x16x32_bf16 v[120:123], v[80:83], v[226:229], v[120:123]
	v_mfma_f32_16x16x32_bf16 v[108:111], v[72:75], v[234:237], v[108:111]
	v_mfma_f32_16x16x32_bf16 v[104:107], v[80:83], v[234:237], v[104:107]
	v_mfma_f32_16x16x32_bf16 v[92:95], v[72:75], v[242:245], v[92:95]
	v_mfma_f32_16x16x32_bf16 v[88:91], v[80:83], v[242:245], v[88:91]
	s_setprio 0
	s_setprio 1
	v_mfma_f32_16x16x32_bf16 v[132:135], v[174:177], v[214:217], v[132:135]
	v_mfma_f32_16x16x32_bf16 v[128:131], v[186:189], v[214:217], v[128:131]
	v_mfma_f32_16x16x32_bf16 v[116:119], v[174:177], v[222:225], v[116:119]
	v_mfma_f32_16x16x32_bf16 v[112:115], v[186:189], v[222:225], v[112:115]
	v_mfma_f32_16x16x32_bf16 v[100:103], v[174:177], v[230:233], v[100:103]
	v_mfma_f32_16x16x32_bf16 v[96:99], v[186:189], v[230:233], v[96:99]
	v_mfma_f32_16x16x32_bf16 v[84:87], v[174:177], v[238:241], v[84:87]
	v_mfma_f32_16x16x32_bf16 v[64:67], v[186:189], v[238:241], v[64:67]
	v_mfma_f32_16x16x32_bf16 v[132:135], v[182:185], v[218:221], v[132:135]
	v_mfma_f32_16x16x32_bf16 v[128:131], v[210:213], v[218:221], v[128:131]
	v_mfma_f32_16x16x32_bf16 v[116:119], v[182:185], v[226:229], v[116:119]
	v_mfma_f32_16x16x32_bf16 v[112:115], v[210:213], v[226:229], v[112:115]
	v_mfma_f32_16x16x32_bf16 v[100:103], v[182:185], v[234:237], v[100:103]
	v_mfma_f32_16x16x32_bf16 v[96:99], v[210:213], v[234:237], v[96:99]
	s_barrier
	v_mfma_f32_16x16x32_bf16 v[84:87], v[182:185], v[242:245], v[84:87]
	v_mfma_f32_16x16x32_bf16 v[64:67], v[210:213], v[242:245], v[64:67]
	s_setprio 0
	s_mov_b32 m0, s30
	v_lshl_add_u64 v[190:191], s[2:3], 0, v[166:167]
	s_add_u32 s58, s2, 0x40000
	ds_read_b128 v[214:217], v179 offset:16384
	ds_read_b128 v[218:221], v179 offset:17408
	ds_read_b128 v[222:225], v179 offset:18432
	ds_read_b128 v[226:229], v179 offset:19456
	ds_read_b128 v[230:233], v179 offset:20480
	ds_read_b128 v[234:237], v179 offset:21504
	ds_read_b128 v[238:241], v179 offset:22528
	ds_read_b128 v[242:245], v179 offset:23552
	global_load_lds_dwordx4 v[190:191], off
	v_lshl_add_u64 v[208:209], s[2:3], 0, v[162:163]
	s_mov_b32 m0, s31
	s_addc_u32 s59, s3, 0
	global_load_lds_dwordx4 v[208:209], off
	v_lshl_add_u64 v[246:247], s[58:59], 0, v[166:167]
	s_mov_b32 m0, s33
	v_lshl_add_u64 v[248:249], s[4:5], 0, v[164:165]
	global_load_lds_dwordx4 v[246:247], off
	v_lshl_add_u64 v[246:247], s[58:59], 0, v[162:163]
	s_mov_b32 m0, s34
	s_nop 0
	global_load_lds_dwordx4 v[246:247], off
	v_lshl_add_u64 v[246:247], s[4:5], 0, v[168:169]
	s_mov_b32 m0, s29
	s_nop 0
	global_load_lds_dwordx4 v[246:247], off
	s_mov_b32 m0, s35
	s_nop 0
	global_load_lds_dwordx4 v[248:249], off
	s_waitcnt vmcnt(8)
	s_waitcnt lgkmcnt(0)
	s_barrier
; #define PG8_STAGE(bufoff, gbase, voff) do { _Pragma("unroll") for (int _i = 0; _i < 2; ++_i) \
;         __builtin_amdgcn_global_load_lds((const unsigned*)((const char*)(gbase) + (voff)[_i]), (PG8_LAS unsigned*)(lds + (bufoff) + ldsw + _i * 8192), 16, 0, 0); } while (0)
; #define PG8_LDA(dst, b, h) do { _Pragma("unroll") for (int m = 0; m < 4; ++m) _Pragma("unroll") for (int k = 0; k < 2; ++k) dst[m][k] = *(const PG8_LAS bf16x8*)(lds + PG8_SA(b, h) + aoff + m * 2048 + k * 1024); } while (0)
; #define PG8_LDB(dst, b, h) do { _Pragma("unroll") for (int n = 0; n < 2; ++n) _Pragma("unroll") for (int k = 0; k < 2; ++k) dst[n][k] = *(const PG8_LAS bf16x8*)(lds + PG8_SB(b, h) + boff + n * 2048 + k * 1024); } while (0)
; #define PG8_MMA(ai, bj, At, Bt) do { __builtin_amdgcn_s_setprio(1); _Pragma("unroll") for (int m = 0; m < 4; ++m) _Pragma("unroll") for (int n = 0; n < 2; ++n) _Pragma("unroll") for (int k = 0; k < 2; ++k) \
;         acc[ai][bj][m][n] = __builtin_amdgcn_mfma_f32_16x16x32_bf16(Bt[n][k], At[m][k], acc[ai][bj][m][n], 0, 0, 0); __builtin_amdgcn_s_setprio(0); } while (0)
; #define PG8_WAIT_V(n) asm volatile("s_waitcnt vmcnt(" #n ")" ::: "memory")
; #define PG8_WAIT_L(n) asm volatile("s_waitcnt lgkmcnt(" #n ")" ::: "memory")
; #define PG8_BAR __builtin_amdgcn_s_barrier()
; #define PG8_SCHED __builtin_amdgcn_sched_barrier(0)
; template <class Epi, class Sched, bool ALIGN_EPI = false, bool SP2 = false>
; __device__ __forceinline__ void gemm_phase(PG8_LAS unsigned char* lds, const Gemm g, const Sched& S, const Epi& E) {
;     ...
;             PG8_WAIT_V(8); PG8_WAIT_L(0); PG8_BAR; PG8_MMA(1, 0, At, B0); PG8_MMA(1, 1, At, B1); PG8_BAR; PG8_SCHED;
;             PG8_LDB(B0, 1, 0); PG8_LDB(B1, 1, 1); PG8_SCHED; PG8_LDA(At, 1, 0); PG8_STAGE(PG8_SA(0, 1), a2 + hstep, voffA);
;             PG8_WAIT_V(8); PG8_WAIT_L(0); PG8_BAR; PG8_MMA(0, 0, At, B0); PG8_MMA(0, 1, At, B1); PG8_BAR; PG8_SCHED;
	s_setprio 1
	s_waitcnt lgkmcnt(0)
	v_mfma_f32_16x16x32_bf16 v[60:63], v[68:71], v[214:217], v[60:63]
	v_mfma_f32_16x16x32_bf16 v[56:59], v[76:79], v[214:217], v[56:59]
	v_mfma_f32_16x16x32_bf16 v[44:47], v[68:71], v[222:225], v[44:47]
	v_mfma_f32_16x16x32_bf16 v[40:43], v[76:79], v[222:225], v[40:43]
	v_mfma_f32_16x16x32_bf16 v[28:31], v[68:71], v[230:233], v[28:31]
	v_mfma_f32_16x16x32_bf16 v[24:27], v[76:79], v[230:233], v[24:27]
	v_mfma_f32_16x16x32_bf16 v[12:15], v[68:71], v[238:241], v[12:15]
	v_mfma_f32_16x16x32_bf16 v[8:11], v[76:79], v[238:241], v[8:11]
	v_mfma_f32_16x16x32_bf16 v[60:63], v[72:75], v[218:221], v[60:63]
	v_mfma_f32_16x16x32_bf16 v[56:59], v[80:83], v[218:221], v[56:59]
	v_mfma_f32_16x16x32_bf16 v[44:47], v[72:75], v[226:229], v[44:47]
	v_mfma_f32_16x16x32_bf16 v[40:43], v[80:83], v[226:229], v[40:43]
	v_mfma_f32_16x16x32_bf16 v[28:31], v[72:75], v[234:237], v[28:31]
	v_mfma_f32_16x16x32_bf16 v[24:27], v[80:83], v[234:237], v[24:27]
	v_mfma_f32_16x16x32_bf16 v[12:15], v[72:75], v[242:245], v[12:15]
	v_mfma_f32_16x16x32_bf16 v[8:11], v[80:83], v[242:245], v[8:11]
	s_setprio 0
	s_setprio 1
	v_mfma_f32_16x16x32_bf16 v[52:55], v[174:177], v[214:217], v[52:55]
	v_mfma_f32_16x16x32_bf16 v[48:51], v[186:189], v[214:217], v[48:51]
	v_mfma_f32_16x16x32_bf16 v[36:39], v[174:177], v[222:225], v[36:39]
	v_mfma_f32_16x16x32_bf16 v[32:35], v[186:189], v[222:225], v[32:35]
	v_mfma_f32_16x16x32_bf16 v[20:23], v[174:177], v[230:233], v[20:23]
	v_mfma_f32_16x16x32_bf16 v[16:19], v[186:189], v[230:233], v[16:19]
	v_mfma_f32_16x16x32_bf16 v[4:7], v[174:177], v[238:241], v[4:7]
	v_mfma_f32_16x16x32_bf16 v[0:3], v[186:189], v[238:241], v[0:3]
	v_mfma_f32_16x16x32_bf16 v[52:55], v[182:185], v[218:221], v[52:55]
	v_mfma_f32_16x16x32_bf16 v[48:51], v[210:213], v[218:221], v[48:51]
	v_mfma_f32_16x16x32_bf16 v[36:39], v[182:185], v[226:229], v[36:39]
	v_mfma_f32_16x16x32_bf16 v[32:35], v[210:213], v[226:229], v[32:35]
	v_mfma_f32_16x16x32_bf16 v[20:23], v[182:185], v[234:237], v[20:23]
	v_mfma_f32_16x16x32_bf16 v[16:19], v[210:213], v[234:237], v[16:19]
	s_barrier
	v_mfma_f32_16x16x32_bf16 v[4:7], v[182:185], v[242:245], v[4:7]
	v_mfma_f32_16x16x32_bf16 v[0:3], v[210:213], v[242:245], v[0:3]
	s_setprio 0
	v_or_b32_e32 v68, 0x18000, v180
	v_add_u32_e32 v72, 0x18400, v180
	v_add_u32_e32 v76, 0x18800, v180
	v_add_u32_e32 v80, 0x18c00, v180
	v_or_b32_e32 v174, 0x1c000, v180
	v_add_u32_e32 v181, 0x1c400, v180
	ds_read_b128 v[68:71], v68
	ds_read_b128 v[72:75], v72
	ds_read_b128 v[76:79], v76
	ds_read_b128 v[80:83], v80
	ds_read_b128 v[174:177], v174
	ds_read_b128 v[182:185], v181
	v_add_u32_e32 v181, 0x1c800, v180
	v_add_u32_e32 v210, 0x1cc00, v180
	ds_read_b128 v[186:189], v181
	ds_read_b128 v[210:213], v210
	s_add_u32 s4, s4, 0x40000
	s_addc_u32 s5, s5, 0
	s_mov_b32 m0, s40
	v_lshl_add_u64 v[250:251], s[4:5], 0, v[168:169]
	ds_read_b128 v[214:217], v179 offset:32768
	ds_read_b128 v[218:221], v179 offset:33792
	ds_read_b128 v[222:225], v179 offset:34816
	ds_read_b128 v[226:229], v179 offset:35840
	ds_read_b128 v[230:233], v179 offset:36864
	ds_read_b128 v[234:237], v179 offset:37888
	ds_read_b128 v[238:241], v179 offset:38912
	ds_read_b128 v[242:245], v179 offset:39936
	global_load_lds_dwordx4 v[250:251], off
	v_lshl_add_u64 v[250:251], s[4:5], 0, v[164:165]
	s_mov_b32 m0, s41
	s_nop 0
	global_load_lds_dwordx4 v[250:251], off
	s_waitcnt vmcnt(8)
	s_waitcnt lgkmcnt(0)
	s_barrier
	s_setprio 1
	s_waitcnt lgkmcnt(0)
	v_mfma_f32_16x16x32_bf16 v[140:143], v[68:71], v[214:217], v[140:143]
	v_mfma_f32_16x16x32_bf16 v[136:139], v[76:79], v[214:217], v[136:139]
	v_mfma_f32_16x16x32_bf16 v[124:127], v[68:71], v[222:225], v[124:127]
	v_mfma_f32_16x16x32_bf16 v[120:123], v[76:79], v[222:225], v[120:123]
	v_mfma_f32_16x16x32_bf16 v[108:111], v[68:71], v[230:233], v[108:111]
	v_mfma_f32_16x16x32_bf16 v[104:107], v[76:79], v[230:233], v[104:107]
	v_mfma_f32_16x16x32_bf16 v[92:95], v[68:71], v[238:241], v[92:95]
	v_mfma_f32_16x16x32_bf16 v[88:91], v[76:79], v[238:241], v[88:91]
	v_mfma_f32_16x16x32_bf16 v[140:143], v[72:75], v[218:221], v[140:143]
	v_mfma_f32_16x16x32_bf16 v[136:139], v[80:83], v[218:221], v[136:139]
	v_mfma_f32_16x16x32_bf16 v[124:127], v[72:75], v[226:229], v[124:127]
	v_mfma_f32_16x16x32_bf16 v[120:123], v[80:83], v[226:229], v[120:123]
	v_mfma_f32_16x16x32_bf16 v[108:111], v[72:75], v[234:237], v[108:111]
	v_mfma_f32_16x16x32_bf16 v[104:107], v[80:83], v[234:237], v[104:107]
	v_mfma_f32_16x16x32_bf16 v[92:95], v[72:75], v[242:245], v[92:95]
	v_mfma_f32_16x16x32_bf16 v[88:91], v[80:83], v[242:245], v[88:91]
	s_setprio 0
	s_setprio 1
	v_mfma_f32_16x16x32_bf16 v[132:135], v[174:177], v[214:217], v[132:135]
	v_mfma_f32_16x16x32_bf16 v[128:131], v[186:189], v[214:217], v[128:131]
	v_mfma_f32_16x16x32_bf16 v[116:119], v[174:177], v[222:225], v[116:119]
	v_mfma_f32_16x16x32_bf16 v[112:115], v[186:189], v[222:225], v[112:115]
	v_mfma_f32_16x16x32_bf16 v[100:103], v[174:177], v[230:233], v[100:103]
	v_mfma_f32_16x16x32_bf16 v[96:99], v[186:189], v[230:233], v[96:99]
	v_mfma_f32_16x16x32_bf16 v[84:87], v[174:177], v[238:241], v[84:87]
	v_mfma_f32_16x16x32_bf16 v[64:67], v[186:189], v[238:241], v[64:67]
	v_mfma_f32_16x16x32_bf16 v[132:135], v[182:185], v[218:221], v[132:135]
	v_mfma_f32_16x16x32_bf16 v[128:131], v[210:213], v[218:221], v[128:131]
	v_mfma_f32_16x16x32_bf16 v[116:119], v[182:185], v[226:229], v[116:119]
	v_mfma_f32_16x16x32_bf16 v[112:115], v[210:213], v[226:229], v[112:115]
	v_mfma_f32_16x16x32_bf16 v[100:103], v[182:185], v[234:237], v[100:103]
	v_mfma_f32_16x16x32_bf16 v[96:99], v[210:213], v[234:237], v[96:99]
	s_barrier
; #define PG8_STAGE(bufoff, gbase, voff) do { _Pragma("unroll") for (int _i = 0; _i < 2; ++_i) \
;         __builtin_amdgcn_global_load_lds((const unsigned*)((const char*)(gbase) + (voff)[_i]), (PG8_LAS unsigned*)(lds + (bufoff) + ldsw + _i * 8192), 16, 0, 0); } while (0)
; #define PG8_LDA(dst, b, h) do { _Pragma("unroll") for (int m = 0; m < 4; ++m) _Pragma("unroll") for (int k = 0; k < 2; ++k) dst[m][k] = *(const PG8_LAS bf16x8*)(lds + PG8_SA(b, h) + aoff + m * 2048 + k * 1024); } while (0)
; #define PG8_MMA(ai, bj, At, Bt) do { __builtin_amdgcn_s_setprio(1); _Pragma("unroll") for (int m = 0; m < 4; ++m) _Pragma("unroll") for (int n = 0; n < 2; ++n) _Pragma("unroll") for (int k = 0; k < 2; ++k) \
;         acc[ai][bj][m][n] = __builtin_amdgcn_mfma_f32_16x16x32_bf16(Bt[n][k], At[m][k], acc[ai][bj][m][n], 0, 0, 0); __builtin_amdgcn_s_setprio(0); } while (0)
; #define PG8_WAIT_V(n) asm volatile("s_waitcnt vmcnt(" #n ")" ::: "memory")
; #define PG8_WAIT_L(n) asm volatile("s_waitcnt lgkmcnt(" #n ")" ::: "memory")
; #define PG8_BAR __builtin_amdgcn_s_barrier()
; #define PG8_SCHED __builtin_amdgcn_sched_barrier(0)
; template <class Epi, class Sched, bool ALIGN_EPI = false, bool SP2 = false>
; __device__ __forceinline__ void gemm_phase(PG8_LAS unsigned char* lds, const Gemm g, const Sched& S, const Epi& E) {
;     ...
;             PG8_WAIT_V(8); PG8_WAIT_L(0); PG8_BAR; PG8_MMA(0, 0, At, B0); PG8_MMA(0, 1, At, B1); PG8_BAR; PG8_SCHED;
;             PG8_LDA(At, 1, 1); PG8_STAGE(PG8_SB(1, 0), b3, voffB); PG8_STAGE(PG8_SB(1, 1), b3 + hstep, voffB); PG8_STAGE(PG8_SA(1, 0), a3, voffA);
;             PG8_WAIT_V(8); PG8_WAIT_L(0); PG8_BAR; PG8_MMA(1, 0, At, B0); PG8_MMA(1, 1, At, B1); PG8_BAR; PG8_SCHED;
	v_mfma_f32_16x16x32_bf16 v[84:87], v[182:185], v[242:245], v[84:87]
	v_mfma_f32_16x16x32_bf16 v[64:67], v[210:213], v[242:245], v[64:67]
	s_setprio 0
	s_mov_b32 m0, s45
	v_lshl_add_u64 v[190:191], v[190:191], 0, s[94:95]
	s_add_u32 s2, s2, 0x40080
	ds_read_b128 v[214:217], v179 offset:49152
	ds_read_b128 v[218:221], v179 offset:50176
	ds_read_b128 v[222:225], v179 offset:51200
	ds_read_b128 v[226:229], v179 offset:52224
	ds_read_b128 v[230:233], v179 offset:53248
	ds_read_b128 v[234:237], v179 offset:54272
	ds_read_b128 v[238:241], v179 offset:55296
	ds_read_b128 v[242:245], v179 offset:56320
	global_load_lds_dwordx4 v[190:191], off
	v_lshl_add_u64 v[190:191], v[208:209], 0, s[94:95]
	s_mov_b32 m0, s46
	s_addc_u32 s3, s3, 0
	global_load_lds_dwordx4 v[190:191], off
	v_lshl_add_u64 v[190:191], s[2:3], 0, v[166:167]
	s_mov_b32 m0, s49
	s_nop 0
	global_load_lds_dwordx4 v[190:191], off
	v_lshl_add_u64 v[190:191], s[2:3], 0, v[162:163]
	s_mov_b32 m0, s50
	s_nop 0
	global_load_lds_dwordx4 v[190:191], off
	v_lshl_add_u64 v[190:191], v[246:247], 0, s[94:95]
	s_mov_b32 m0, s47
	s_nop 0
	global_load_lds_dwordx4 v[190:191], off
	v_lshl_add_u64 v[190:191], v[248:249], 0, s[94:95]
	s_mov_b32 m0, s48
	s_nop 0
	global_load_lds_dwordx4 v[190:191], off
	s_waitcnt vmcnt(8)
	s_waitcnt lgkmcnt(0)
	s_barrier
	s_setprio 1
	s_waitcnt lgkmcnt(0)
	v_mfma_f32_16x16x32_bf16 v[60:63], v[68:71], v[214:217], v[60:63]
	v_mfma_f32_16x16x32_bf16 v[56:59], v[76:79], v[214:217], v[56:59]
	v_mfma_f32_16x16x32_bf16 v[44:47], v[68:71], v[222:225], v[44:47]
	v_mfma_f32_16x16x32_bf16 v[40:43], v[76:79], v[222:225], v[40:43]
	v_mfma_f32_16x16x32_bf16 v[28:31], v[68:71], v[230:233], v[28:31]
	v_mfma_f32_16x16x32_bf16 v[24:27], v[76:79], v[230:233], v[24:27]
	v_mfma_f32_16x16x32_bf16 v[12:15], v[68:71], v[238:241], v[12:15]
	v_mfma_f32_16x16x32_bf16 v[8:11], v[76:79], v[238:241], v[8:11]
	v_mfma_f32_16x16x32_bf16 v[60:63], v[72:75], v[218:221], v[60:63]
	v_mfma_f32_16x16x32_bf16 v[56:59], v[80:83], v[218:221], v[56:59]
	v_mfma_f32_16x16x32_bf16 v[44:47], v[72:75], v[226:229], v[44:47]
	v_mfma_f32_16x16x32_bf16 v[40:43], v[80:83], v[226:229], v[40:43]
	v_mfma_f32_16x16x32_bf16 v[28:31], v[72:75], v[234:237], v[28:31]
	v_mfma_f32_16x16x32_bf16 v[24:27], v[80:83], v[234:237], v[24:27]
	v_mfma_f32_16x16x32_bf16 v[12:15], v[72:75], v[242:245], v[12:15]
	v_mfma_f32_16x16x32_bf16 v[8:11], v[80:83], v[242:245], v[8:11]
	s_setprio 0
	s_setprio 1
	v_mfma_f32_16x16x32_bf16 v[52:55], v[174:177], v[214:217], v[52:55]
	v_mfma_f32_16x16x32_bf16 v[48:51], v[186:189], v[214:217], v[48:51]
	v_mfma_f32_16x16x32_bf16 v[36:39], v[174:177], v[222:225], v[36:39]
	v_mfma_f32_16x16x32_bf16 v[32:35], v[186:189], v[222:225], v[32:35]
	v_mfma_f32_16x16x32_bf16 v[20:23], v[174:177], v[230:233], v[20:23]
	v_mfma_f32_16x16x32_bf16 v[16:19], v[186:189], v[230:233], v[16:19]
	v_mfma_f32_16x16x32_bf16 v[4:7], v[174:177], v[238:241], v[4:7]
	v_mfma_f32_16x16x32_bf16 v[0:3], v[186:189], v[238:241], v[0:3]
	v_mfma_f32_16x16x32_bf16 v[52:55], v[182:185], v[218:221], v[52:55]
	v_mfma_f32_16x16x32_bf16 v[48:51], v[210:213], v[218:221], v[48:51]
	v_mfma_f32_16x16x32_bf16 v[36:39], v[182:185], v[226:229], v[36:39]
	v_mfma_f32_16x16x32_bf16 v[32:35], v[210:213], v[226:229], v[32:35]
	v_mfma_f32_16x16x32_bf16 v[20:23], v[182:185], v[234:237], v[20:23]
	v_mfma_f32_16x16x32_bf16 v[16:19], v[210:213], v[234:237], v[16:19]
	s_barrier
	v_mfma_f32_16x16x32_bf16 v[4:7], v[182:185], v[242:245], v[4:7]
	v_mfma_f32_16x16x32_bf16 v[0:3], v[210:213], v[242:245], v[0:3]
	s_setprio 0
	s_add_i32 s56, s56, 2
	s_add_u32 s0, s0, 0x100
	s_addc_u32 s1, s1, 0
	s_add_u32 s54, s54, 0x100
	s_addc_u32 s55, s55, 0
	s_cmp_gt_u32 s56, 13
	s_cbranch_scc0 .LBB0_327
	s_and_b64 vcc, exec, s[22:23]
	s_cbranch_vccz .LBB0_330
	s_barrier

; #define PG8_STAGE(bufoff, gbase, voff) do { _Pragma("unroll") for (int _i = 0; _i < 2; ++_i) \
;         __builtin_amdgcn_global_load_lds((const unsigned*)((const char*)(gbase) + (voff)[_i]), (PG8_LAS unsigned*)(lds + (bufoff) + ldsw + _i * 8192), 16, 0, 0); } while (0)
; #define PG8_LDA(dst, b, h) do { _Pragma("unroll") for (int m = 0; m < 4; ++m) _Pragma("unroll") for (int k = 0; k < 2; ++k) dst[m][k] = *(const PG8_LAS bf16x8*)(lds + PG8_SA(b, h) + aoff + m * 2048 + k * 1024); } while (0)
; #define PG8_LDB(dst, b, h) do { _Pragma("unroll") for (int n = 0; n < 2; ++n) _Pragma("unroll") for (int k = 0; k < 2; ++k) dst[n][k] = *(const PG8_LAS bf16x8*)(lds + PG8_SB(b, h) + boff + n * 2048 + k * 1024); } while (0)
; #define PG8_MMA(ai, bj, At, Bt) do { __builtin_amdgcn_s_setprio(1); _Pragma("unroll") for (int m = 0; m < 4; ++m) _Pragma("unroll") for (int n = 0; n < 2; ++n) _Pragma("unroll") for (int k = 0; k < 2; ++k) \
;         acc[ai][bj][m][n] = __builtin_amdgcn_mfma_f32_16x16x32_bf16(Bt[n][k], At[m][k], acc[ai][bj][m][n], 0, 0, 0); __builtin_amdgcn_s_setprio(0); } while (0)
; #define PG8_WAIT_V(n) asm volatile("s_waitcnt vmcnt(" #n ")" ::: "memory")
; #define PG8_WAIT_L(n) asm volatile("s_waitcnt lgkmcnt(" #n ")" ::: "memory")
; #define PG8_BAR __builtin_amdgcn_s_barrier()
; #define PG8_SCHED __builtin_amdgcn_sched_barrier(0)
; template <class Epi, class Sched, bool ALIGN_EPI = false, bool SP2 = false>
; __device__ __forceinline__ void gemm_phase(PG8_LAS unsigned char* lds, const Gemm g, const Sched& S, const Epi& E) {
;     ...
;             const bool last = (t == nt - 2);
;             const char* a1 = cA + (size_t)(t + 1) * kstep;
;             const char* a2 = last ? nA : cA + (size_t)(t + 2) * kstep; const char* b2 = last ? nB : cB + (size_t)(t + 2) * kstep;
;             const char* a3 = a2 + kstep; const char* b3 = b2 + kstep;
;             if (last && has_next) S.a_ready(nxt);
;             if constexpr (SP2) {
;             PG8_LDB(B0, 0, 0); PG8_LDB(B1, 0, 1); PG8_SCHED; PG8_LDA(At, 0, 0); PG8_STAGE(PG8_SA(1, 1), a1 + hstep, voffA);
;             PG8_WAIT_V(8); PG8_WAIT_L(0); PG8_BAR; PG8_MMA(0, 0, At, B0); PG8_MMA(0, 1, At, B1); PG8_BAR; PG8_SCHED;
;             PG8_LDA(At, 0, 1); PG8_STAGE(PG8_SB(0, 0), b2, voffB); PG8_STAGE(PG8_SB(0, 1), b2 + hstep, voffB); PG8_STAGE(PG8_SA(0, 0), a2, voffA);
.LBB0_446:
	v_or_b32_e32 v140, 0x10000, v166
	v_add_u32_e32 v162, 0x10400, v166
	ds_read_b128 v[140:143], v140
	ds_read_b128 v[168:171], v162
	v_add_u32_e32 v162, 0x10800, v166
	v_add_u32_e32 v163, 0x10c00, v166
	ds_read_b128 v[172:175], v162
	ds_read_b128 v[176:179], v163
	v_or_b32_e32 v162, 0x14000, v166
	v_add_u32_e32 v163, 0x14400, v166
	ds_read_b128 v[180:183], v162
	ds_read_b128 v[184:187], v163
	v_add_u32_e32 v162, 0x14800, v166
	v_add_u32_e32 v163, 0x14c00, v166
	ds_read_b128 v[188:191], v162
	ds_read_b128 v[210:213], v163
	s_add_u32 s16, s14, 0xfffc0080
	s_addc_u32 s17, s15, -1
	s_cmp_eq_u32 s53, 12
	s_cselect_b32 s19, s7, s17
	s_cselect_b32 s18, s49, s16
	s_cselect_b32 s17, s5, s52
	s_cselect_b32 s16, s50, s51
	s_mov_b32 m0, s43
	v_lshl_add_u64 v[162:163], s[14:15], 0, v[136:137]
	ds_read_b128 v[214:217], v165
	ds_read_b128 v[218:221], v165 offset:1024
	ds_read_b128 v[222:225], v165 offset:2048
	ds_read_b128 v[226:229], v165 offset:3072
	ds_read_b128 v[230:233], v165 offset:4096
	ds_read_b128 v[234:237], v165 offset:5120
	ds_read_b128 v[238:241], v165 offset:6144
	ds_read_b128 v[242:245], v165 offset:7168
	global_load_lds_dwordx4 v[162:163], off
	v_lshl_add_u64 v[162:163], s[14:15], 0, v[138:139]
	s_mov_b32 m0, s44
	s_nop 0
	global_load_lds_dwordx4 v[162:163], off
	s_waitcnt vmcnt(8)
	s_waitcnt lgkmcnt(0)
	s_barrier
	s_setprio 1
	s_waitcnt lgkmcnt(0)
	v_mfma_f32_16x16x32_bf16 v[124:127], v[140:143], v[214:217], v[124:127]
	v_mfma_f32_16x16x32_bf16 v[116:119], v[172:175], v[214:217], v[116:119]
	v_mfma_f32_16x16x32_bf16 v[108:111], v[140:143], v[222:225], v[108:111]
	v_mfma_f32_16x16x32_bf16 v[100:103], v[172:175], v[222:225], v[100:103]
	v_mfma_f32_16x16x32_bf16 v[92:95], v[140:143], v[230:233], v[92:95]
	v_mfma_f32_16x16x32_bf16 v[84:87], v[172:175], v[230:233], v[84:87]
	v_mfma_f32_16x16x32_bf16 v[76:79], v[140:143], v[238:241], v[76:79]
	v_mfma_f32_16x16x32_bf16 v[68:71], v[172:175], v[238:241], v[68:71]
	v_mfma_f32_16x16x32_bf16 v[124:127], v[168:171], v[218:221], v[124:127]
	v_mfma_f32_16x16x32_bf16 v[116:119], v[176:179], v[218:221], v[116:119]
	v_mfma_f32_16x16x32_bf16 v[108:111], v[168:171], v[226:229], v[108:111]
	v_mfma_f32_16x16x32_bf16 v[100:103], v[176:179], v[226:229], v[100:103]
	v_mfma_f32_16x16x32_bf16 v[92:95], v[168:171], v[234:237], v[92:95]
	v_mfma_f32_16x16x32_bf16 v[84:87], v[176:179], v[234:237], v[84:87]
	v_mfma_f32_16x16x32_bf16 v[76:79], v[168:171], v[242:245], v[76:79]
	v_mfma_f32_16x16x32_bf16 v[68:71], v[176:179], v[242:245], v[68:71]
	s_setprio 0
	s_setprio 1
	v_mfma_f32_16x16x32_bf16 v[120:123], v[180:183], v[214:217], v[120:123]
	v_mfma_f32_16x16x32_bf16 v[112:115], v[188:191], v[214:217], v[112:115]
	v_mfma_f32_16x16x32_bf16 v[104:107], v[180:183], v[222:225], v[104:107]
	v_mfma_f32_16x16x32_bf16 v[96:99], v[188:191], v[222:225], v[96:99]
	v_mfma_f32_16x16x32_bf16 v[88:91], v[180:183], v[230:233], v[88:91]
	v_mfma_f32_16x16x32_bf16 v[80:83], v[188:191], v[230:233], v[80:83]
	v_mfma_f32_16x16x32_bf16 v[72:75], v[180:183], v[238:241], v[72:75]
	v_mfma_f32_16x16x32_bf16 v[64:67], v[188:191], v[238:241], v[64:67]
	v_mfma_f32_16x16x32_bf16 v[120:123], v[184:187], v[218:221], v[120:123]
	v_mfma_f32_16x16x32_bf16 v[112:115], v[210:213], v[218:221], v[112:115]
	v_mfma_f32_16x16x32_bf16 v[104:107], v[184:187], v[226:229], v[104:107]
	v_mfma_f32_16x16x32_bf16 v[96:99], v[210:213], v[226:229], v[96:99]
	v_mfma_f32_16x16x32_bf16 v[88:91], v[184:187], v[234:237], v[88:91]
	v_mfma_f32_16x16x32_bf16 v[80:83], v[210:213], v[234:237], v[80:83]
	s_barrier
	v_mfma_f32_16x16x32_bf16 v[72:75], v[184:187], v[242:245], v[72:75]
	v_mfma_f32_16x16x32_bf16 v[64:67], v[210:213], v[242:245], v[64:67]
	s_setprio 0
	s_mov_b32 m0, s27
	v_lshl_add_u64 v[162:163], s[16:17], 0, v[132:133]
	s_add_u32 s54, s16, 0x40000
	ds_read_b128 v[214:217], v165 offset:16384
	ds_read_b128 v[218:221], v165 offset:17408
	ds_read_b128 v[222:225], v165 offset:18432
	ds_read_b128 v[226:229], v165 offset:19456
	ds_read_b128 v[230:233], v165 offset:20480
	ds_read_b128 v[234:237], v165 offset:21504
	ds_read_b128 v[238:241], v165 offset:22528
	ds_read_b128 v[242:245], v165 offset:23552
	global_load_lds_dwordx4 v[162:163], off
	v_lshl_add_u64 v[246:247], s[16:17], 0, v[128:129]
	s_mov_b32 m0, s28
	s_addc_u32 s55, s17, 0
	global_load_lds_dwordx4 v[246:247], off
	v_lshl_add_u64 v[248:249], s[54:55], 0, v[132:133]
	s_mov_b32 m0, s29
	v_lshl_add_u64 v[250:251], s[18:19], 0, v[130:131]
	global_load_lds_dwordx4 v[248:249], off
	v_lshl_add_u64 v[248:249], s[54:55], 0, v[128:129]
	s_mov_b32 m0, s30
	s_nop 0
	global_load_lds_dwordx4 v[248:249], off
	v_lshl_add_u64 v[248:249], s[18:19], 0, v[134:135]
	s_mov_b32 m0, s22
	s_nop 0
	global_load_lds_dwordx4 v[248:249], off
	s_mov_b32 m0, s31
	s_nop 0
	global_load_lds_dwordx4 v[250:251], off
	s_waitcnt vmcnt(8)
	s_waitcnt lgkmcnt(0)
	s_barrier
; #define PG8_STAGE(bufoff, gbase, voff) do { _Pragma("unroll") for (int _i = 0; _i < 2; ++_i) \
;         __builtin_amdgcn_global_load_lds((const unsigned*)((const char*)(gbase) + (voff)[_i]), (PG8_LAS unsigned*)(lds + (bufoff) + ldsw + _i * 8192), 16, 0, 0); } while (0)
; #define PG8_LDA(dst, b, h) do { _Pragma("unroll") for (int m = 0; m < 4; ++m) _Pragma("unroll") for (int k = 0; k < 2; ++k) dst[m][k] = *(const PG8_LAS bf16x8*)(lds + PG8_SA(b, h) + aoff + m * 2048 + k * 1024); } while (0)
; #define PG8_LDB(dst, b, h) do { _Pragma("unroll") for (int n = 0; n < 2; ++n) _Pragma("unroll") for (int k = 0; k < 2; ++k) dst[n][k] = *(const PG8_LAS bf16x8*)(lds + PG8_SB(b, h) + boff + n * 2048 + k * 1024); } while (0)
; #define PG8_MMA(ai, bj, At, Bt) do { __builtin_amdgcn_s_setprio(1); _Pragma("unroll") for (int m = 0; m < 4; ++m) _Pragma("unroll") for (int n = 0; n < 2; ++n) _Pragma("unroll") for (int k = 0; k < 2; ++k) \
;         acc[ai][bj][m][n] = __builtin_amdgcn_mfma_f32_16x16x32_bf16(Bt[n][k], At[m][k], acc[ai][bj][m][n], 0, 0, 0); __builtin_amdgcn_s_setprio(0); } while (0)
; #define PG8_WAIT_V(n) asm volatile("s_waitcnt vmcnt(" #n ")" ::: "memory")
; #define PG8_WAIT_L(n) asm volatile("s_waitcnt lgkmcnt(" #n ")" ::: "memory")
; #define PG8_BAR __builtin_amdgcn_s_barrier()
; #define PG8_SCHED __builtin_amdgcn_sched_barrier(0)
; template <class Epi, class Sched, bool ALIGN_EPI = false, bool SP2 = false>
; __device__ __forceinline__ void gemm_phase(PG8_LAS unsigned char* lds, const Gemm g, const Sched& S, const Epi& E) {
;     ...
;             PG8_WAIT_V(8); PG8_WAIT_L(0); PG8_BAR; PG8_MMA(1, 0, At, B0); PG8_MMA(1, 1, At, B1); PG8_BAR; PG8_SCHED;
;             PG8_LDB(B0, 1, 0); PG8_LDB(B1, 1, 1); PG8_SCHED; PG8_LDA(At, 1, 0); PG8_STAGE(PG8_SA(0, 1), a2 + hstep, voffA);
;             PG8_WAIT_V(8); PG8_WAIT_L(0); PG8_BAR; PG8_MMA(0, 0, At, B0); PG8_MMA(0, 1, At, B1); PG8_BAR; PG8_SCHED;
	s_setprio 1
	s_waitcnt lgkmcnt(0)
	v_mfma_f32_16x16x32_bf16 v[60:63], v[140:143], v[214:217], v[60:63]
	v_mfma_f32_16x16x32_bf16 v[52:55], v[172:175], v[214:217], v[52:55]
	v_mfma_f32_16x16x32_bf16 v[44:47], v[140:143], v[222:225], v[44:47]
	v_mfma_f32_16x16x32_bf16 v[36:39], v[172:175], v[222:225], v[36:39]
	v_mfma_f32_16x16x32_bf16 v[28:31], v[140:143], v[230:233], v[28:31]
	v_mfma_f32_16x16x32_bf16 v[20:23], v[172:175], v[230:233], v[20:23]
	v_mfma_f32_16x16x32_bf16 v[12:15], v[140:143], v[238:241], v[12:15]
	v_mfma_f32_16x16x32_bf16 v[4:7], v[172:175], v[238:241], v[4:7]
	v_mfma_f32_16x16x32_bf16 v[60:63], v[168:171], v[218:221], v[60:63]
	v_mfma_f32_16x16x32_bf16 v[52:55], v[176:179], v[218:221], v[52:55]
	v_mfma_f32_16x16x32_bf16 v[44:47], v[168:171], v[226:229], v[44:47]
	v_mfma_f32_16x16x32_bf16 v[36:39], v[176:179], v[226:229], v[36:39]
	v_mfma_f32_16x16x32_bf16 v[28:31], v[168:171], v[234:237], v[28:31]
	v_mfma_f32_16x16x32_bf16 v[20:23], v[176:179], v[234:237], v[20:23]
	v_mfma_f32_16x16x32_bf16 v[12:15], v[168:171], v[242:245], v[12:15]
	v_mfma_f32_16x16x32_bf16 v[4:7], v[176:179], v[242:245], v[4:7]
	s_setprio 0
	s_setprio 1
	v_mfma_f32_16x16x32_bf16 v[56:59], v[180:183], v[214:217], v[56:59]
	v_mfma_f32_16x16x32_bf16 v[48:51], v[188:191], v[214:217], v[48:51]
	v_mfma_f32_16x16x32_bf16 v[40:43], v[180:183], v[222:225], v[40:43]
	v_mfma_f32_16x16x32_bf16 v[32:35], v[188:191], v[222:225], v[32:35]
	v_mfma_f32_16x16x32_bf16 v[24:27], v[180:183], v[230:233], v[24:27]
	v_mfma_f32_16x16x32_bf16 v[16:19], v[188:191], v[230:233], v[16:19]
	v_mfma_f32_16x16x32_bf16 v[8:11], v[180:183], v[238:241], v[8:11]
	v_mfma_f32_16x16x32_bf16 v[0:3], v[188:191], v[238:241], v[0:3]
	v_mfma_f32_16x16x32_bf16 v[56:59], v[184:187], v[218:221], v[56:59]
	v_mfma_f32_16x16x32_bf16 v[48:51], v[210:213], v[218:221], v[48:51]
	v_mfma_f32_16x16x32_bf16 v[40:43], v[184:187], v[226:229], v[40:43]
	v_mfma_f32_16x16x32_bf16 v[32:35], v[210:213], v[226:229], v[32:35]
	v_mfma_f32_16x16x32_bf16 v[24:27], v[184:187], v[234:237], v[24:27]
	v_mfma_f32_16x16x32_bf16 v[16:19], v[210:213], v[234:237], v[16:19]
	s_barrier
	v_mfma_f32_16x16x32_bf16 v[8:11], v[184:187], v[242:245], v[8:11]
	v_mfma_f32_16x16x32_bf16 v[0:3], v[210:213], v[242:245], v[0:3]
	s_setprio 0
	v_or_b32_e32 v140, 0x18000, v166
	v_add_u32_e32 v167, 0x18400, v166
	ds_read_b128 v[140:143], v140
	ds_read_b128 v[168:171], v167
	v_add_u32_e32 v167, 0x18800, v166
	v_add_u32_e32 v176, 0x18c00, v166
	ds_read_b128 v[172:175], v167
	ds_read_b128 v[176:179], v176
	v_or_b32_e32 v167, 0x1c000, v166
	v_add_u32_e32 v184, 0x1c400, v166
	ds_read_b128 v[180:183], v167
	ds_read_b128 v[184:187], v184
	v_add_u32_e32 v167, 0x1c800, v166
	v_add_u32_e32 v208, 0x1cc00, v166
	ds_read_b128 v[188:191], v167
	ds_read_b128 v[210:213], v208
	s_add_u32 s18, s18, 0x40000
	s_addc_u32 s19, s19, 0
	s_mov_b32 m0, s33
	v_lshl_add_u64 v[208:209], s[18:19], 0, v[134:135]
	ds_read_b128 v[214:217], v165 offset:32768
	ds_read_b128 v[218:221], v165 offset:33792
	ds_read_b128 v[222:225], v165 offset:34816
	ds_read_b128 v[226:229], v165 offset:35840
	ds_read_b128 v[230:233], v165 offset:36864
	ds_read_b128 v[234:237], v165 offset:37888
	ds_read_b128 v[238:241], v165 offset:38912
	ds_read_b128 v[242:245], v165 offset:39936
	global_load_lds_dwordx4 v[208:209], off
	v_lshl_add_u64 v[208:209], s[18:19], 0, v[130:131]
	s_mov_b32 m0, s34
	s_nop 0
	global_load_lds_dwordx4 v[208:209], off
	s_waitcnt vmcnt(8)
	s_waitcnt lgkmcnt(0)
	s_barrier
	s_setprio 1
	s_waitcnt lgkmcnt(0)
	v_mfma_f32_16x16x32_bf16 v[124:127], v[140:143], v[214:217], v[124:127]
	v_mfma_f32_16x16x32_bf16 v[116:119], v[172:175], v[214:217], v[116:119]
	v_mfma_f32_16x16x32_bf16 v[108:111], v[140:143], v[222:225], v[108:111]
	v_mfma_f32_16x16x32_bf16 v[100:103], v[172:175], v[222:225], v[100:103]
	v_mfma_f32_16x16x32_bf16 v[92:95], v[140:143], v[230:233], v[92:95]
	v_mfma_f32_16x16x32_bf16 v[84:87], v[172:175], v[230:233], v[84:87]
	v_mfma_f32_16x16x32_bf16 v[76:79], v[140:143], v[238:241], v[76:79]
	v_mfma_f32_16x16x32_bf16 v[68:71], v[172:175], v[238:241], v[68:71]
	v_mfma_f32_16x16x32_bf16 v[124:127], v[168:171], v[218:221], v[124:127]
	v_mfma_f32_16x16x32_bf16 v[116:119], v[176:179], v[218:221], v[116:119]
	v_mfma_f32_16x16x32_bf16 v[108:111], v[168:171], v[226:229], v[108:111]
	v_mfma_f32_16x16x32_bf16 v[100:103], v[176:179], v[226:229], v[100:103]
	v_mfma_f32_16x16x32_bf16 v[92:95], v[168:171], v[234:237], v[92:95]
	v_mfma_f32_16x16x32_bf16 v[84:87], v[176:179], v[234:237], v[84:87]
	v_mfma_f32_16x16x32_bf16 v[76:79], v[168:171], v[242:245], v[76:79]
	v_mfma_f32_16x16x32_bf16 v[68:71], v[176:179], v[242:245], v[68:71]
	s_setprio 0
	s_setprio 1
	v_mfma_f32_16x16x32_bf16 v[120:123], v[180:183], v[214:217], v[120:123]
	v_mfma_f32_16x16x32_bf16 v[112:115], v[188:191], v[214:217], v[112:115]
	v_mfma_f32_16x16x32_bf16 v[104:107], v[180:183], v[222:225], v[104:107]
	v_mfma_f32_16x16x32_bf16 v[96:99], v[188:191], v[222:225], v[96:99]
	v_mfma_f32_16x16x32_bf16 v[88:91], v[180:183], v[230:233], v[88:91]
	v_mfma_f32_16x16x32_bf16 v[80:83], v[188:191], v[230:233], v[80:83]
	v_mfma_f32_16x16x32_bf16 v[72:75], v[180:183], v[238:241], v[72:75]
	v_mfma_f32_16x16x32_bf16 v[64:67], v[188:191], v[238:241], v[64:67]
	v_mfma_f32_16x16x32_bf16 v[120:123], v[184:187], v[218:221], v[120:123]
	v_mfma_f32_16x16x32_bf16 v[112:115], v[210:213], v[218:221], v[112:115]
	v_mfma_f32_16x16x32_bf16 v[104:107], v[184:187], v[226:229], v[104:107]
	v_mfma_f32_16x16x32_bf16 v[96:99], v[210:213], v[226:229], v[96:99]
	v_mfma_f32_16x16x32_bf16 v[88:91], v[184:187], v[234:237], v[88:91]
	v_mfma_f32_16x16x32_bf16 v[80:83], v[210:213], v[234:237], v[80:83]
	s_barrier
; #define PG8_STAGE(bufoff, gbase, voff) do { _Pragma("unroll") for (int _i = 0; _i < 2; ++_i) \
;         __builtin_amdgcn_global_load_lds((const unsigned*)((const char*)(gbase) + (voff)[_i]), (PG8_LAS unsigned*)(lds + (bufoff) + ldsw + _i * 8192), 16, 0, 0); } while (0)
; #define PG8_LDA(dst, b, h) do { _Pragma("unroll") for (int m = 0; m < 4; ++m) _Pragma("unroll") for (int k = 0; k < 2; ++k) dst[m][k] = *(const PG8_LAS bf16x8*)(lds + PG8_SA(b, h) + aoff + m * 2048 + k * 1024); } while (0)
; #define PG8_MMA(ai, bj, At, Bt) do { __builtin_amdgcn_s_setprio(1); _Pragma("unroll") for (int m = 0; m < 4; ++m) _Pragma("unroll") for (int n = 0; n < 2; ++n) _Pragma("unroll") for (int k = 0; k < 2; ++k) \
;         acc[ai][bj][m][n] = __builtin_amdgcn_mfma_f32_16x16x32_bf16(Bt[n][k], At[m][k], acc[ai][bj][m][n], 0, 0, 0); __builtin_amdgcn_s_setprio(0); } while (0)
; #define PG8_WAIT_V(n) asm volatile("s_waitcnt vmcnt(" #n ")" ::: "memory")
; #define PG8_WAIT_L(n) asm volatile("s_waitcnt lgkmcnt(" #n ")" ::: "memory")
; #define PG8_BAR __builtin_amdgcn_s_barrier()
; #define PG8_SCHED __builtin_amdgcn_sched_barrier(0)
; template <class Epi, class Sched, bool ALIGN_EPI = false, bool SP2 = false>
; __device__ __forceinline__ void gemm_phase(PG8_LAS unsigned char* lds, const Gemm g, const Sched& S, const Epi& E) {
;     ...
;             PG8_WAIT_V(8); PG8_WAIT_L(0); PG8_BAR; PG8_MMA(0, 0, At, B0); PG8_MMA(0, 1, At, B1); PG8_BAR; PG8_SCHED;
;             PG8_LDA(At, 1, 1); PG8_STAGE(PG8_SB(1, 0), b3, voffB); PG8_STAGE(PG8_SB(1, 1), b3 + hstep, voffB); PG8_STAGE(PG8_SA(1, 0), a3, voffA);
;             PG8_WAIT_V(8); PG8_WAIT_L(0); PG8_BAR; PG8_MMA(1, 0, At, B0); PG8_MMA(1, 1, At, B1); PG8_BAR; PG8_SCHED;
	v_mfma_f32_16x16x32_bf16 v[72:75], v[184:187], v[242:245], v[72:75]
	v_mfma_f32_16x16x32_bf16 v[64:67], v[210:213], v[242:245], v[64:67]
	s_setprio 0
	s_mov_b32 m0, s37
	v_lshl_add_u64 v[162:163], v[162:163], 0, s[94:95]
	s_add_u32 s16, s16, 0x40080
	ds_read_b128 v[214:217], v165 offset:49152
	ds_read_b128 v[218:221], v165 offset:50176
	ds_read_b128 v[222:225], v165 offset:51200
	ds_read_b128 v[226:229], v165 offset:52224
	ds_read_b128 v[230:233], v165 offset:53248
	ds_read_b128 v[234:237], v165 offset:54272
	ds_read_b128 v[238:241], v165 offset:55296
	ds_read_b128 v[242:245], v165 offset:56320
	global_load_lds_dwordx4 v[162:163], off
	v_lshl_add_u64 v[162:163], v[246:247], 0, s[94:95]
	s_mov_b32 m0, s38
	s_addc_u32 s17, s17, 0
	global_load_lds_dwordx4 v[162:163], off
	v_lshl_add_u64 v[162:163], s[16:17], 0, v[132:133]
	s_mov_b32 m0, s41
	s_nop 0
	global_load_lds_dwordx4 v[162:163], off
	v_lshl_add_u64 v[162:163], s[16:17], 0, v[128:129]
	s_mov_b32 m0, s42
	s_nop 0
	global_load_lds_dwordx4 v[162:163], off
	v_lshl_add_u64 v[162:163], v[248:249], 0, s[94:95]
	s_mov_b32 m0, s39
	s_nop 0
	global_load_lds_dwordx4 v[162:163], off
	v_lshl_add_u64 v[162:163], v[250:251], 0, s[94:95]
	s_mov_b32 m0, s40
	s_nop 0
	global_load_lds_dwordx4 v[162:163], off
	s_waitcnt vmcnt(8)
	s_waitcnt lgkmcnt(0)
	s_barrier
	s_setprio 1
	s_waitcnt lgkmcnt(0)
	v_mfma_f32_16x16x32_bf16 v[60:63], v[140:143], v[214:217], v[60:63]
	v_mfma_f32_16x16x32_bf16 v[52:55], v[172:175], v[214:217], v[52:55]
	v_mfma_f32_16x16x32_bf16 v[44:47], v[140:143], v[222:225], v[44:47]
	v_mfma_f32_16x16x32_bf16 v[36:39], v[172:175], v[222:225], v[36:39]
	v_mfma_f32_16x16x32_bf16 v[28:31], v[140:143], v[230:233], v[28:31]
	v_mfma_f32_16x16x32_bf16 v[20:23], v[172:175], v[230:233], v[20:23]
	v_mfma_f32_16x16x32_bf16 v[12:15], v[140:143], v[238:241], v[12:15]
	v_mfma_f32_16x16x32_bf16 v[4:7], v[172:175], v[238:241], v[4:7]
	v_mfma_f32_16x16x32_bf16 v[60:63], v[168:171], v[218:221], v[60:63]
	v_mfma_f32_16x16x32_bf16 v[52:55], v[176:179], v[218:221], v[52:55]
	v_mfma_f32_16x16x32_bf16 v[44:47], v[168:171], v[226:229], v[44:47]
	v_mfma_f32_16x16x32_bf16 v[36:39], v[176:179], v[226:229], v[36:39]
	v_mfma_f32_16x16x32_bf16 v[28:31], v[168:171], v[234:237], v[28:31]
	v_mfma_f32_16x16x32_bf16 v[20:23], v[176:179], v[234:237], v[20:23]
	v_mfma_f32_16x16x32_bf16 v[12:15], v[168:171], v[242:245], v[12:15]
	v_mfma_f32_16x16x32_bf16 v[4:7], v[176:179], v[242:245], v[4:7]
	s_setprio 0
	s_setprio 1
	v_mfma_f32_16x16x32_bf16 v[56:59], v[180:183], v[214:217], v[56:59]
	v_mfma_f32_16x16x32_bf16 v[48:51], v[188:191], v[214:217], v[48:51]
	v_mfma_f32_16x16x32_bf16 v[40:43], v[180:183], v[222:225], v[40:43]
	v_mfma_f32_16x16x32_bf16 v[32:35], v[188:191], v[222:225], v[32:35]
	v_mfma_f32_16x16x32_bf16 v[24:27], v[180:183], v[230:233], v[24:27]
	v_mfma_f32_16x16x32_bf16 v[16:19], v[188:191], v[230:233], v[16:19]
	v_mfma_f32_16x16x32_bf16 v[8:11], v[180:183], v[238:241], v[8:11]
	v_mfma_f32_16x16x32_bf16 v[0:3], v[188:191], v[238:241], v[0:3]
	v_mfma_f32_16x16x32_bf16 v[56:59], v[184:187], v[218:221], v[56:59]
	v_mfma_f32_16x16x32_bf16 v[48:51], v[210:213], v[218:221], v[48:51]
	v_mfma_f32_16x16x32_bf16 v[40:43], v[184:187], v[226:229], v[40:43]
	v_mfma_f32_16x16x32_bf16 v[32:35], v[210:213], v[226:229], v[32:35]
	v_mfma_f32_16x16x32_bf16 v[24:27], v[184:187], v[234:237], v[24:27]
	v_mfma_f32_16x16x32_bf16 v[16:19], v[210:213], v[234:237], v[16:19]
	s_barrier
	v_mfma_f32_16x16x32_bf16 v[8:11], v[184:187], v[242:245], v[8:11]
	v_mfma_f32_16x16x32_bf16 v[0:3], v[210:213], v[242:245], v[0:3]
	s_setprio 0
	s_add_i32 s53, s53, 2
	s_add_u32 s14, s14, 0x100
	s_addc_u32 s15, s15, 0
	s_add_u32 s51, s51, 0x100
	s_addc_u32 s52, s52, 0
	s_cmp_gt_u32 s53, 13
	s_cbranch_scc0 .LBB0_446
	s_and_b64 vcc, exec, s[2:3]
	s_cbranch_vccz .LBB0_449
	s_barrier

; #define PG8_STAGE(bufoff, gbase, voff) do { _Pragma("unroll") for (int _i = 0; _i < 2; ++_i) \
;         __builtin_amdgcn_global_load_lds((const unsigned*)((const char*)(gbase) + (voff)[_i]), (PG8_LAS unsigned*)(lds + (bufoff) + ldsw + _i * 8192), 16, 0, 0); } while (0)
; #define PG8_LDA(dst, b, h) do { _Pragma("unroll") for (int m = 0; m < 4; ++m) _Pragma("unroll") for (int k = 0; k < 2; ++k) dst[m][k] = *(const PG8_LAS bf16x8*)(lds + PG8_SA(b, h) + aoff + m * 2048 + k * 1024); } while (0)
; #define PG8_LDB(dst, b, h) do { _Pragma("unroll") for (int n = 0; n < 2; ++n) _Pragma("unroll") for (int k = 0; k < 2; ++k) dst[n][k] = *(const PG8_LAS bf16x8*)(lds + PG8_SB(b, h) + boff + n * 2048 + k * 1024); } while (0)
; #define PG8_MMA(ai, bj, At, Bt) do { __builtin_amdgcn_s_setprio(1); _Pragma("unroll") for (int m = 0; m < 4; ++m) _Pragma("unroll") for (int n = 0; n < 2; ++n) _Pragma("unroll") for (int k = 0; k < 2; ++k) \
;         acc[ai][bj][m][n] = __builtin_amdgcn_mfma_f32_16x16x32_bf16(Bt[n][k], At[m][k], acc[ai][bj][m][n], 0, 0, 0); __builtin_amdgcn_s_setprio(0); } while (0)
; #define PG8_WAIT_V(n) asm volatile("s_waitcnt vmcnt(" #n ")" ::: "memory")
; #define PG8_WAIT_L(n) asm volatile("s_waitcnt lgkmcnt(" #n ")" ::: "memory")
; #define PG8_BAR __builtin_amdgcn_s_barrier()
; #define PG8_SCHED __builtin_amdgcn_sched_barrier(0)
; template <class Epi, class Sched, bool ALIGN_EPI = false, bool SP2 = false>
; __device__ __forceinline__ void gemm_phase(PG8_LAS unsigned char* lds, const Gemm g, const Sched& S, const Epi& E) {
;     ...
;             const bool last = (t == nt - 2);
;             const char* a1 = cA + (size_t)(t + 1) * kstep;
;             const char* a2 = last ? nA : cA + (size_t)(t + 2) * kstep; const char* b2 = last ? nB : cB + (size_t)(t + 2) * kstep;
;             const char* a3 = a2 + kstep; const char* b3 = b2 + kstep;
;             if (last && has_next) S.a_ready(nxt);
;             if constexpr (SP2) {
;             PG8_LDB(B0, 0, 0); PG8_LDB(B1, 0, 1); PG8_SCHED; PG8_LDA(At, 0, 0); PG8_STAGE(PG8_SA(1, 1), a1 + hstep, voffA);
;             PG8_WAIT_V(8); PG8_WAIT_L(0); PG8_BAR; PG8_MMA(0, 0, At, B0); PG8_MMA(0, 1, At, B1); PG8_BAR; PG8_SCHED;
;             PG8_LDA(At, 0, 1); PG8_STAGE(PG8_SB(0, 0), b2, voffB); PG8_STAGE(PG8_SB(0, 1), b2 + hstep, voffB); PG8_STAGE(PG8_SA(0, 0), a2, voffA);
.LBB0_545:
	v_or_b32_e32 v128, 0x10000, v182
	v_add_u32_e32 v132, 0x10400, v182
	v_add_u32_e32 v136, 0x10800, v182
	v_add_u32_e32 v140, 0x10c00, v182
	v_or_b32_e32 v174, 0x14000, v182
	v_add_u32_e32 v178, 0x14400, v182
	ds_read_b128 v[128:131], v128
	ds_read_b128 v[132:135], v132
	ds_read_b128 v[136:139], v136
	ds_read_b128 v[140:143], v140
	ds_read_b128 v[174:177], v174
	ds_read_b128 v[184:187], v178
	v_add_u32_e32 v178, 0x14800, v182
	v_add_u32_e32 v179, 0x14c00, v182
	ds_read_b128 v[188:191], v178
	ds_read_b128 v[210:213], v179
	s_add_u32 s2, s0, 0x100
	s_addc_u32 s3, s1, 0
	s_cmp_eq_u32 s13, 40
	s_cselect_b32 s7, s27, s3
	s_cselect_b32 s6, s26, s2
	s_cselect_b32 s5, s37, s11
	s_cselect_b32 s4, s36, s10
	v_lshl_add_u64 v[178:179], s[0:1], 0, v[170:171]
	s_add_i32 m0, s29, 0xc000
	ds_read_b128 v[214:217], v181
	ds_read_b128 v[218:221], v181 offset:1024
	ds_read_b128 v[222:225], v181 offset:2048
	ds_read_b128 v[226:229], v181 offset:3072
	ds_read_b128 v[230:233], v181 offset:4096
	ds_read_b128 v[234:237], v181 offset:5120
	ds_read_b128 v[238:241], v181 offset:6144
	ds_read_b128 v[242:245], v181 offset:7168
	global_load_lds_dwordx4 v[178:179], off
	v_lshl_add_u64 v[178:179], s[0:1], 0, v[172:173]
	s_add_i32 m0, s29, 0xe000
	s_nop 0
	global_load_lds_dwordx4 v[178:179], off
	s_waitcnt vmcnt(8)
	s_waitcnt lgkmcnt(0)
	s_barrier
	s_setprio 1
	s_waitcnt lgkmcnt(0)
	v_mfma_f32_16x16x32_bf16 v[124:127], v[128:131], v[214:217], v[124:127]
	v_mfma_f32_16x16x32_bf16 v[120:123], v[136:139], v[214:217], v[120:123]
	v_mfma_f32_16x16x32_bf16 v[108:111], v[128:131], v[222:225], v[108:111]
	v_mfma_f32_16x16x32_bf16 v[104:107], v[136:139], v[222:225], v[104:107]
	v_mfma_f32_16x16x32_bf16 v[92:95], v[128:131], v[230:233], v[92:95]
	v_mfma_f32_16x16x32_bf16 v[88:91], v[136:139], v[230:233], v[88:91]
	v_mfma_f32_16x16x32_bf16 v[76:79], v[128:131], v[238:241], v[76:79]
	v_mfma_f32_16x16x32_bf16 v[72:75], v[136:139], v[238:241], v[72:75]
	v_mfma_f32_16x16x32_bf16 v[124:127], v[132:135], v[218:221], v[124:127]
	v_mfma_f32_16x16x32_bf16 v[120:123], v[140:143], v[218:221], v[120:123]
	v_mfma_f32_16x16x32_bf16 v[108:111], v[132:135], v[226:229], v[108:111]
	v_mfma_f32_16x16x32_bf16 v[104:107], v[140:143], v[226:229], v[104:107]
	v_mfma_f32_16x16x32_bf16 v[92:95], v[132:135], v[234:237], v[92:95]
	v_mfma_f32_16x16x32_bf16 v[88:91], v[140:143], v[234:237], v[88:91]
	v_mfma_f32_16x16x32_bf16 v[76:79], v[132:135], v[242:245], v[76:79]
	v_mfma_f32_16x16x32_bf16 v[72:75], v[140:143], v[242:245], v[72:75]
	s_setprio 0
	s_setprio 1
	v_mfma_f32_16x16x32_bf16 v[116:119], v[174:177], v[214:217], v[116:119]
	v_mfma_f32_16x16x32_bf16 v[112:115], v[188:191], v[214:217], v[112:115]
	v_mfma_f32_16x16x32_bf16 v[100:103], v[174:177], v[222:225], v[100:103]
	v_mfma_f32_16x16x32_bf16 v[96:99], v[188:191], v[222:225], v[96:99]
	v_mfma_f32_16x16x32_bf16 v[84:87], v[174:177], v[230:233], v[84:87]
	v_mfma_f32_16x16x32_bf16 v[80:83], v[188:191], v[230:233], v[80:83]
	v_mfma_f32_16x16x32_bf16 v[68:71], v[174:177], v[238:241], v[68:71]
	v_mfma_f32_16x16x32_bf16 v[64:67], v[188:191], v[238:241], v[64:67]
	v_mfma_f32_16x16x32_bf16 v[116:119], v[184:187], v[218:221], v[116:119]
	v_mfma_f32_16x16x32_bf16 v[112:115], v[210:213], v[218:221], v[112:115]
	v_mfma_f32_16x16x32_bf16 v[100:103], v[184:187], v[226:229], v[100:103]
	v_mfma_f32_16x16x32_bf16 v[96:99], v[210:213], v[226:229], v[96:99]
	v_mfma_f32_16x16x32_bf16 v[84:87], v[184:187], v[234:237], v[84:87]
	v_mfma_f32_16x16x32_bf16 v[80:83], v[210:213], v[234:237], v[80:83]
	s_barrier
	v_mfma_f32_16x16x32_bf16 v[68:71], v[184:187], v[242:245], v[68:71]
	v_mfma_f32_16x16x32_bf16 v[64:67], v[210:213], v[242:245], v[64:67]
	s_setprio 0
	s_mov_b32 m0, s35
	v_lshl_add_u64 v[178:179], s[4:5], 0, v[166:167]
	s_add_u32 s0, s4, 0xb0000
	ds_read_b128 v[214:217], v181 offset:16384
	ds_read_b128 v[218:221], v181 offset:17408
	ds_read_b128 v[222:225], v181 offset:18432
	ds_read_b128 v[226:229], v181 offset:19456
	ds_read_b128 v[230:233], v181 offset:20480
	ds_read_b128 v[234:237], v181 offset:21504
	ds_read_b128 v[238:241], v181 offset:22528
	ds_read_b128 v[242:245], v181 offset:23552
	global_load_lds_dwordx4 v[178:179], off
	v_lshl_add_u64 v[208:209], s[4:5], 0, v[162:163]
	s_mov_b32 m0, s38
	s_addc_u32 s1, s5, 0
	global_load_lds_dwordx4 v[208:209], off
	v_lshl_add_u64 v[246:247], s[0:1], 0, v[166:167]
	s_mov_b32 m0, s39
	v_lshl_add_u64 v[248:249], s[6:7], 0, v[164:165]
	global_load_lds_dwordx4 v[246:247], off
	v_lshl_add_u64 v[246:247], s[0:1], 0, v[162:163]
	s_mov_b32 m0, s40
	s_nop 0
	global_load_lds_dwordx4 v[246:247], off
	v_lshl_add_u64 v[246:247], s[6:7], 0, v[168:169]
	s_mov_b32 m0, s29
	s_nop 0
	global_load_lds_dwordx4 v[246:247], off
	s_mov_b32 m0, s41
	s_nop 0
	global_load_lds_dwordx4 v[248:249], off
	s_waitcnt vmcnt(8)
	s_waitcnt lgkmcnt(0)
	s_barrier
; #define PG8_STAGE(bufoff, gbase, voff) do { _Pragma("unroll") for (int _i = 0; _i < 2; ++_i) \
;         __builtin_amdgcn_global_load_lds((const unsigned*)((const char*)(gbase) + (voff)[_i]), (PG8_LAS unsigned*)(lds + (bufoff) + ldsw + _i * 8192), 16, 0, 0); } while (0)
; #define PG8_LDA(dst, b, h) do { _Pragma("unroll") for (int m = 0; m < 4; ++m) _Pragma("unroll") for (int k = 0; k < 2; ++k) dst[m][k] = *(const PG8_LAS bf16x8*)(lds + PG8_SA(b, h) + aoff + m * 2048 + k * 1024); } while (0)
; #define PG8_LDB(dst, b, h) do { _Pragma("unroll") for (int n = 0; n < 2; ++n) _Pragma("unroll") for (int k = 0; k < 2; ++k) dst[n][k] = *(const PG8_LAS bf16x8*)(lds + PG8_SB(b, h) + boff + n * 2048 + k * 1024); } while (0)
; #define PG8_MMA(ai, bj, At, Bt) do { __builtin_amdgcn_s_setprio(1); _Pragma("unroll") for (int m = 0; m < 4; ++m) _Pragma("unroll") for (int n = 0; n < 2; ++n) _Pragma("unroll") for (int k = 0; k < 2; ++k) \
;         acc[ai][bj][m][n] = __builtin_amdgcn_mfma_f32_16x16x32_bf16(Bt[n][k], At[m][k], acc[ai][bj][m][n], 0, 0, 0); __builtin_amdgcn_s_setprio(0); } while (0)
; #define PG8_WAIT_V(n) asm volatile("s_waitcnt vmcnt(" #n ")" ::: "memory")
; #define PG8_WAIT_L(n) asm volatile("s_waitcnt lgkmcnt(" #n ")" ::: "memory")
; #define PG8_BAR __builtin_amdgcn_s_barrier()
; #define PG8_SCHED __builtin_amdgcn_sched_barrier(0)
; template <class Epi, class Sched, bool ALIGN_EPI = false, bool SP2 = false>
; __device__ __forceinline__ void gemm_phase(PG8_LAS unsigned char* lds, const Gemm g, const Sched& S, const Epi& E) {
;     ...
;             PG8_WAIT_V(8); PG8_WAIT_L(0); PG8_BAR; PG8_MMA(1, 0, At, B0); PG8_MMA(1, 1, At, B1); PG8_BAR; PG8_SCHED;
;             PG8_LDB(B0, 1, 0); PG8_LDB(B1, 1, 1); PG8_SCHED; PG8_LDA(At, 1, 0); PG8_STAGE(PG8_SA(0, 1), a2 + hstep, voffA);
;             PG8_WAIT_V(8); PG8_WAIT_L(0); PG8_BAR; PG8_MMA(0, 0, At, B0); PG8_MMA(0, 1, At, B1); PG8_BAR; PG8_SCHED;
	s_setprio 1
	s_waitcnt lgkmcnt(0)
	v_mfma_f32_16x16x32_bf16 v[60:63], v[128:131], v[214:217], v[60:63]
	v_mfma_f32_16x16x32_bf16 v[56:59], v[136:139], v[214:217], v[56:59]
	v_mfma_f32_16x16x32_bf16 v[44:47], v[128:131], v[222:225], v[44:47]
	v_mfma_f32_16x16x32_bf16 v[40:43], v[136:139], v[222:225], v[40:43]
	v_mfma_f32_16x16x32_bf16 v[28:31], v[128:131], v[230:233], v[28:31]
	v_mfma_f32_16x16x32_bf16 v[24:27], v[136:139], v[230:233], v[24:27]
	v_mfma_f32_16x16x32_bf16 v[12:15], v[128:131], v[238:241], v[12:15]
	v_mfma_f32_16x16x32_bf16 v[8:11], v[136:139], v[238:241], v[8:11]
	v_mfma_f32_16x16x32_bf16 v[60:63], v[132:135], v[218:221], v[60:63]
	v_mfma_f32_16x16x32_bf16 v[56:59], v[140:143], v[218:221], v[56:59]
	v_mfma_f32_16x16x32_bf16 v[44:47], v[132:135], v[226:229], v[44:47]
	v_mfma_f32_16x16x32_bf16 v[40:43], v[140:143], v[226:229], v[40:43]
	v_mfma_f32_16x16x32_bf16 v[28:31], v[132:135], v[234:237], v[28:31]
	v_mfma_f32_16x16x32_bf16 v[24:27], v[140:143], v[234:237], v[24:27]
	v_mfma_f32_16x16x32_bf16 v[12:15], v[132:135], v[242:245], v[12:15]
	v_mfma_f32_16x16x32_bf16 v[8:11], v[140:143], v[242:245], v[8:11]
	s_setprio 0
	s_setprio 1
	v_mfma_f32_16x16x32_bf16 v[52:55], v[174:177], v[214:217], v[52:55]
	v_mfma_f32_16x16x32_bf16 v[48:51], v[188:191], v[214:217], v[48:51]
	v_mfma_f32_16x16x32_bf16 v[36:39], v[174:177], v[222:225], v[36:39]
	v_mfma_f32_16x16x32_bf16 v[32:35], v[188:191], v[222:225], v[32:35]
	v_mfma_f32_16x16x32_bf16 v[20:23], v[174:177], v[230:233], v[20:23]
	v_mfma_f32_16x16x32_bf16 v[16:19], v[188:191], v[230:233], v[16:19]
	v_mfma_f32_16x16x32_bf16 v[4:7], v[174:177], v[238:241], v[4:7]
	v_mfma_f32_16x16x32_bf16 v[0:3], v[188:191], v[238:241], v[0:3]
	v_mfma_f32_16x16x32_bf16 v[52:55], v[184:187], v[218:221], v[52:55]
	v_mfma_f32_16x16x32_bf16 v[48:51], v[210:213], v[218:221], v[48:51]
	v_mfma_f32_16x16x32_bf16 v[36:39], v[184:187], v[226:229], v[36:39]
	v_mfma_f32_16x16x32_bf16 v[32:35], v[210:213], v[226:229], v[32:35]
	v_mfma_f32_16x16x32_bf16 v[20:23], v[184:187], v[234:237], v[20:23]
	v_mfma_f32_16x16x32_bf16 v[16:19], v[210:213], v[234:237], v[16:19]
	s_barrier
	v_mfma_f32_16x16x32_bf16 v[4:7], v[184:187], v[242:245], v[4:7]
	v_mfma_f32_16x16x32_bf16 v[0:3], v[210:213], v[242:245], v[0:3]
	s_setprio 0
	v_or_b32_e32 v128, 0x18000, v182
	v_add_u32_e32 v132, 0x18400, v182
	v_add_u32_e32 v136, 0x18800, v182
	v_add_u32_e32 v140, 0x18c00, v182
	v_or_b32_e32 v174, 0x1c000, v182
	v_add_u32_e32 v183, 0x1c400, v182
	ds_read_b128 v[128:131], v128
	ds_read_b128 v[132:135], v132
	ds_read_b128 v[136:139], v136
	ds_read_b128 v[140:143], v140
	ds_read_b128 v[174:177], v174
	ds_read_b128 v[184:187], v183
	v_add_u32_e32 v183, 0x1c800, v182
	v_add_u32_e32 v210, 0x1cc00, v182
	ds_read_b128 v[188:191], v183
	ds_read_b128 v[210:213], v210
	s_add_u32 s0, s6, 0xb0000
	s_addc_u32 s1, s7, 0
	s_mov_b32 m0, s42
	v_lshl_add_u64 v[250:251], s[0:1], 0, v[168:169]
	ds_read_b128 v[214:217], v181 offset:32768
	ds_read_b128 v[218:221], v181 offset:33792
	ds_read_b128 v[222:225], v181 offset:34816
	ds_read_b128 v[226:229], v181 offset:35840
	ds_read_b128 v[230:233], v181 offset:36864
	ds_read_b128 v[234:237], v181 offset:37888
	ds_read_b128 v[238:241], v181 offset:38912
	ds_read_b128 v[242:245], v181 offset:39936
	global_load_lds_dwordx4 v[250:251], off
	v_lshl_add_u64 v[250:251], s[0:1], 0, v[164:165]
	s_mov_b32 m0, s43
	s_nop 0
	global_load_lds_dwordx4 v[250:251], off
	s_waitcnt vmcnt(8)
	s_waitcnt lgkmcnt(0)
	s_barrier
	s_setprio 1
	s_waitcnt lgkmcnt(0)
	v_mfma_f32_16x16x32_bf16 v[124:127], v[128:131], v[214:217], v[124:127]
	v_mfma_f32_16x16x32_bf16 v[120:123], v[136:139], v[214:217], v[120:123]
	v_mfma_f32_16x16x32_bf16 v[108:111], v[128:131], v[222:225], v[108:111]
	v_mfma_f32_16x16x32_bf16 v[104:107], v[136:139], v[222:225], v[104:107]
	v_mfma_f32_16x16x32_bf16 v[92:95], v[128:131], v[230:233], v[92:95]
	v_mfma_f32_16x16x32_bf16 v[88:91], v[136:139], v[230:233], v[88:91]
	v_mfma_f32_16x16x32_bf16 v[76:79], v[128:131], v[238:241], v[76:79]
	v_mfma_f32_16x16x32_bf16 v[72:75], v[136:139], v[238:241], v[72:75]
	v_mfma_f32_16x16x32_bf16 v[124:127], v[132:135], v[218:221], v[124:127]
	v_mfma_f32_16x16x32_bf16 v[120:123], v[140:143], v[218:221], v[120:123]
	v_mfma_f32_16x16x32_bf16 v[108:111], v[132:135], v[226:229], v[108:111]
	v_mfma_f32_16x16x32_bf16 v[104:107], v[140:143], v[226:229], v[104:107]
	v_mfma_f32_16x16x32_bf16 v[92:95], v[132:135], v[234:237], v[92:95]
	v_mfma_f32_16x16x32_bf16 v[88:91], v[140:143], v[234:237], v[88:91]
	v_mfma_f32_16x16x32_bf16 v[76:79], v[132:135], v[242:245], v[76:79]
	v_mfma_f32_16x16x32_bf16 v[72:75], v[140:143], v[242:245], v[72:75]
	s_setprio 0
	s_setprio 1
	v_mfma_f32_16x16x32_bf16 v[116:119], v[174:177], v[214:217], v[116:119]
	v_mfma_f32_16x16x32_bf16 v[112:115], v[188:191], v[214:217], v[112:115]
	v_mfma_f32_16x16x32_bf16 v[100:103], v[174:177], v[222:225], v[100:103]
	v_mfma_f32_16x16x32_bf16 v[96:99], v[188:191], v[222:225], v[96:99]
	v_mfma_f32_16x16x32_bf16 v[84:87], v[174:177], v[230:233], v[84:87]
	v_mfma_f32_16x16x32_bf16 v[80:83], v[188:191], v[230:233], v[80:83]
	v_mfma_f32_16x16x32_bf16 v[68:71], v[174:177], v[238:241], v[68:71]
	v_mfma_f32_16x16x32_bf16 v[64:67], v[188:191], v[238:241], v[64:67]
	v_mfma_f32_16x16x32_bf16 v[116:119], v[184:187], v[218:221], v[116:119]
	v_mfma_f32_16x16x32_bf16 v[112:115], v[210:213], v[218:221], v[112:115]
	v_mfma_f32_16x16x32_bf16 v[100:103], v[184:187], v[226:229], v[100:103]
	v_mfma_f32_16x16x32_bf16 v[96:99], v[210:213], v[226:229], v[96:99]
	v_mfma_f32_16x16x32_bf16 v[84:87], v[184:187], v[234:237], v[84:87]
	v_mfma_f32_16x16x32_bf16 v[80:83], v[210:213], v[234:237], v[80:83]
	s_barrier
; #define PG8_STAGE(bufoff, gbase, voff) do { _Pragma("unroll") for (int _i = 0; _i < 2; ++_i) \
;         __builtin_amdgcn_global_load_lds((const unsigned*)((const char*)(gbase) + (voff)[_i]), (PG8_LAS unsigned*)(lds + (bufoff) + ldsw + _i * 8192), 16, 0, 0); } while (0)
; #define PG8_LDA(dst, b, h) do { _Pragma("unroll") for (int m = 0; m < 4; ++m) _Pragma("unroll") for (int k = 0; k < 2; ++k) dst[m][k] = *(const PG8_LAS bf16x8*)(lds + PG8_SA(b, h) + aoff + m * 2048 + k * 1024); } while (0)
; #define PG8_MMA(ai, bj, At, Bt) do { __builtin_amdgcn_s_setprio(1); _Pragma("unroll") for (int m = 0; m < 4; ++m) _Pragma("unroll") for (int n = 0; n < 2; ++n) _Pragma("unroll") for (int k = 0; k < 2; ++k) \
;         acc[ai][bj][m][n] = __builtin_amdgcn_mfma_f32_16x16x32_bf16(Bt[n][k], At[m][k], acc[ai][bj][m][n], 0, 0, 0); __builtin_amdgcn_s_setprio(0); } while (0)
; #define PG8_WAIT_V(n) asm volatile("s_waitcnt vmcnt(" #n ")" ::: "memory")
; #define PG8_WAIT_L(n) asm volatile("s_waitcnt lgkmcnt(" #n ")" ::: "memory")
; #define PG8_BAR __builtin_amdgcn_s_barrier()
; #define PG8_SCHED __builtin_amdgcn_sched_barrier(0)
; template <class Epi, class Sched, bool ALIGN_EPI = false, bool SP2 = false>
; __device__ __forceinline__ void gemm_phase(PG8_LAS unsigned char* lds, const Gemm g, const Sched& S, const Epi& E) {
;     ...
;             PG8_WAIT_V(8); PG8_WAIT_L(0); PG8_BAR; PG8_MMA(0, 0, At, B0); PG8_MMA(0, 1, At, B1); PG8_BAR; PG8_SCHED;
;             PG8_LDA(At, 1, 1); PG8_STAGE(PG8_SB(1, 0), b3, voffB); PG8_STAGE(PG8_SB(1, 1), b3 + hstep, voffB); PG8_STAGE(PG8_SA(1, 0), a3, voffA);
;             PG8_WAIT_V(8); PG8_WAIT_L(0); PG8_BAR; PG8_MMA(1, 0, At, B0); PG8_MMA(1, 1, At, B1); PG8_BAR; PG8_SCHED;
	v_mfma_f32_16x16x32_bf16 v[68:71], v[184:187], v[242:245], v[68:71]
	v_mfma_f32_16x16x32_bf16 v[64:67], v[210:213], v[242:245], v[64:67]
	s_setprio 0
	s_mov_b32 m0, s47
	v_lshl_add_u64 v[178:179], v[178:179], 0, s[94:95]
	s_add_u32 s0, s4, 0xb0080
	ds_read_b128 v[214:217], v181 offset:49152
	ds_read_b128 v[218:221], v181 offset:50176
	ds_read_b128 v[222:225], v181 offset:51200
	ds_read_b128 v[226:229], v181 offset:52224
	ds_read_b128 v[230:233], v181 offset:53248
	ds_read_b128 v[234:237], v181 offset:54272
	ds_read_b128 v[238:241], v181 offset:55296
	ds_read_b128 v[242:245], v181 offset:56320
	global_load_lds_dwordx4 v[178:179], off
	v_lshl_add_u64 v[178:179], v[208:209], 0, s[94:95]
	s_mov_b32 m0, s48
	s_addc_u32 s1, s5, 0
	global_load_lds_dwordx4 v[178:179], off
	v_lshl_add_u64 v[178:179], s[0:1], 0, v[166:167]
	s_mov_b32 m0, s51
	s_nop 0
	global_load_lds_dwordx4 v[178:179], off
	v_lshl_add_u64 v[178:179], s[0:1], 0, v[162:163]
	s_mov_b32 m0, s52
	s_nop 0
	global_load_lds_dwordx4 v[178:179], off
	v_lshl_add_u64 v[178:179], v[246:247], 0, s[94:95]
	s_mov_b32 m0, s49
	s_nop 0
	global_load_lds_dwordx4 v[178:179], off
	v_lshl_add_u64 v[178:179], v[248:249], 0, s[94:95]
	s_mov_b32 m0, s50
	s_nop 0
	global_load_lds_dwordx4 v[178:179], off
	s_waitcnt vmcnt(8)
	s_waitcnt lgkmcnt(0)
	s_barrier
	s_setprio 1
	s_waitcnt lgkmcnt(0)
	v_mfma_f32_16x16x32_bf16 v[60:63], v[128:131], v[214:217], v[60:63]
	v_mfma_f32_16x16x32_bf16 v[56:59], v[136:139], v[214:217], v[56:59]
	v_mfma_f32_16x16x32_bf16 v[44:47], v[128:131], v[222:225], v[44:47]
	v_mfma_f32_16x16x32_bf16 v[40:43], v[136:139], v[222:225], v[40:43]
	v_mfma_f32_16x16x32_bf16 v[28:31], v[128:131], v[230:233], v[28:31]
	v_mfma_f32_16x16x32_bf16 v[24:27], v[136:139], v[230:233], v[24:27]
	v_mfma_f32_16x16x32_bf16 v[12:15], v[128:131], v[238:241], v[12:15]
	v_mfma_f32_16x16x32_bf16 v[8:11], v[136:139], v[238:241], v[8:11]
	v_mfma_f32_16x16x32_bf16 v[60:63], v[132:135], v[218:221], v[60:63]
	v_mfma_f32_16x16x32_bf16 v[56:59], v[140:143], v[218:221], v[56:59]
	v_mfma_f32_16x16x32_bf16 v[44:47], v[132:135], v[226:229], v[44:47]
	v_mfma_f32_16x16x32_bf16 v[40:43], v[140:143], v[226:229], v[40:43]
	v_mfma_f32_16x16x32_bf16 v[28:31], v[132:135], v[234:237], v[28:31]
	v_mfma_f32_16x16x32_bf16 v[24:27], v[140:143], v[234:237], v[24:27]
	v_mfma_f32_16x16x32_bf16 v[12:15], v[132:135], v[242:245], v[12:15]
	v_mfma_f32_16x16x32_bf16 v[8:11], v[140:143], v[242:245], v[8:11]
	s_setprio 0
	s_setprio 1
	v_mfma_f32_16x16x32_bf16 v[52:55], v[174:177], v[214:217], v[52:55]
	v_mfma_f32_16x16x32_bf16 v[48:51], v[188:191], v[214:217], v[48:51]
	v_mfma_f32_16x16x32_bf16 v[36:39], v[174:177], v[222:225], v[36:39]
	v_mfma_f32_16x16x32_bf16 v[32:35], v[188:191], v[222:225], v[32:35]
	v_mfma_f32_16x16x32_bf16 v[20:23], v[174:177], v[230:233], v[20:23]
	v_mfma_f32_16x16x32_bf16 v[16:19], v[188:191], v[230:233], v[16:19]
	v_mfma_f32_16x16x32_bf16 v[4:7], v[174:177], v[238:241], v[4:7]
	v_mfma_f32_16x16x32_bf16 v[0:3], v[188:191], v[238:241], v[0:3]
	v_mfma_f32_16x16x32_bf16 v[52:55], v[184:187], v[218:221], v[52:55]
	v_mfma_f32_16x16x32_bf16 v[48:51], v[210:213], v[218:221], v[48:51]
	v_mfma_f32_16x16x32_bf16 v[36:39], v[184:187], v[226:229], v[36:39]
	v_mfma_f32_16x16x32_bf16 v[32:35], v[210:213], v[226:229], v[32:35]
	v_mfma_f32_16x16x32_bf16 v[20:23], v[184:187], v[234:237], v[20:23]
	v_mfma_f32_16x16x32_bf16 v[16:19], v[210:213], v[234:237], v[16:19]
	s_barrier
	v_mfma_f32_16x16x32_bf16 v[4:7], v[184:187], v[242:245], v[4:7]
	v_mfma_f32_16x16x32_bf16 v[0:3], v[210:213], v[242:245], v[0:3]
	s_setprio 0
	s_add_i32 s13, s13, 2
	s_add_u32 s10, s10, 0x100
	s_addc_u32 s11, s11, 0
	s_cmp_gt_u32 s13, 41
	s_mov_b64 s[0:1], s[2:3]
	s_cbranch_scc0 .LBB0_545
	s_and_b64 vcc, exec, s[22:23]
	s_cbranch_vccz .LBB0_548
	s_barrier

; #define PG8_STAGE(bufoff, gbase, voff) do { _Pragma("unroll") for (int _i = 0; _i < 2; ++_i) \
;         __builtin_amdgcn_global_load_lds((const unsigned*)((const char*)(gbase) + (voff)[_i]), (PG8_LAS unsigned*)(lds + (bufoff) + ldsw + _i * 8192), 16, 0, 0); } while (0)
; #define PG8_LDA(dst, b, h) do { _Pragma("unroll") for (int m = 0; m < 4; ++m) _Pragma("unroll") for (int k = 0; k < 2; ++k) dst[m][k] = *(const PG8_LAS bf16x8*)(lds + PG8_SA(b, h) + aoff + m * 2048 + k * 1024); } while (0)
; #define PG8_LDB(dst, b, h) do { _Pragma("unroll") for (int n = 0; n < 2; ++n) _Pragma("unroll") for (int k = 0; k < 2; ++k) dst[n][k] = *(const PG8_LAS bf16x8*)(lds + PG8_SB(b, h) + boff + n * 2048 + k * 1024); } while (0)
; #define PG8_MMA(ai, bj, At, Bt) do { __builtin_amdgcn_s_setprio(1); _Pragma("unroll") for (int m = 0; m < 4; ++m) _Pragma("unroll") for (int n = 0; n < 2; ++n) _Pragma("unroll") for (int k = 0; k < 2; ++k) \
;         acc[ai][bj][m][n] = __builtin_amdgcn_mfma_f32_16x16x32_bf16(Bt[n][k], At[m][k], acc[ai][bj][m][n], 0, 0, 0); __builtin_amdgcn_s_setprio(0); } while (0)
; #define PG8_WAIT_V(n) asm volatile("s_waitcnt vmcnt(" #n ")" ::: "memory")
; #define PG8_WAIT_L(n) asm volatile("s_waitcnt lgkmcnt(" #n ")" ::: "memory")
; #define PG8_BAR __builtin_amdgcn_s_barrier()
; #define PG8_SCHED __builtin_amdgcn_sched_barrier(0)
; template <class Epi, class Sched, bool ALIGN_EPI = false, bool SP2 = false>
; __device__ __forceinline__ void gemm_phase(PG8_LAS unsigned char* lds, const Gemm g, const Sched& S, const Epi& E) {
;     ...
;             const bool last = (t == nt - 2);
;             const char* a1 = cA + (size_t)(t + 1) * kstep;
;             const char* a2 = last ? nA : cA + (size_t)(t + 2) * kstep; const char* b2 = last ? nB : cB + (size_t)(t + 2) * kstep;
;             const char* a3 = a2 + kstep; const char* b3 = b2 + kstep;
;             if (last && has_next) S.a_ready(nxt);
;             if constexpr (SP2) {
;             PG8_LDB(B0, 0, 0); PG8_LDB(B1, 0, 1); PG8_SCHED; PG8_LDA(At, 0, 0); PG8_STAGE(PG8_SA(1, 1), a1 + hstep, voffA);
;             PG8_WAIT_V(8); PG8_WAIT_L(0); PG8_BAR; PG8_MMA(0, 0, At, B0); PG8_MMA(0, 1, At, B1); PG8_BAR; PG8_SCHED;
;             PG8_LDA(At, 0, 1); PG8_STAGE(PG8_SB(0, 0), b2, voffB); PG8_STAGE(PG8_SB(0, 1), b2 + hstep, voffB); PG8_STAGE(PG8_SA(0, 0), a2, voffA);
.LBB0_749:
	v_or_b32_e32 v140, 0x10000, v179
	v_add_u32_e32 v147, 0x10400, v179
	ds_read_b128 v[140:143], v140
	ds_read_b128 v[162:165], v147
	v_add_u32_e32 v147, 0x10800, v179
	v_add_u32_e32 v170, 0x10c00, v179
	ds_read_b128 v[166:169], v147
	ds_read_b128 v[170:173], v170
	v_or_b32_e32 v147, 0x14000, v179
	v_add_u32_e32 v174, 0x14400, v179
	ds_read_b128 v[180:183], v147
	ds_read_b128 v[184:187], v174
	v_add_u32_e32 v147, 0x14800, v179
	v_add_u32_e32 v174, 0x14c00, v179
	ds_read_b128 v[188:191], v147
	ds_read_b128 v[210:213], v174
	s_add_u32 s2, s0, 0xfffc0080
	s_addc_u32 s3, s1, -1
	s_cmp_eq_u32 s55, 12
	s_cselect_b32 s5, s13, s3
	s_cselect_b32 s4, s25, s2
	s_cselect_b32 s3, s23, s39
	s_cselect_b32 s2, s33, s38
	v_lshl_add_u64 v[174:175], s[0:1], 0, v[136:137]
	s_add_i32 m0, s6, 0xc000
	ds_read_b128 v[214:217], v178
	ds_read_b128 v[218:221], v178 offset:1024
	ds_read_b128 v[222:225], v178 offset:2048
	ds_read_b128 v[226:229], v178 offset:3072
	ds_read_b128 v[230:233], v178 offset:4096
	ds_read_b128 v[234:237], v178 offset:5120
	ds_read_b128 v[238:241], v178 offset:6144
	ds_read_b128 v[242:245], v178 offset:7168
	global_load_lds_dwordx4 v[174:175], off
	v_lshl_add_u64 v[174:175], s[0:1], 0, v[138:139]
	s_add_i32 m0, s6, 0xe000
	s_nop 0
	global_load_lds_dwordx4 v[174:175], off
	s_waitcnt vmcnt(8)
	s_waitcnt lgkmcnt(0)
	s_barrier
	s_setprio 1
	s_waitcnt lgkmcnt(0)
	v_mfma_f32_16x16x32_bf16 v[124:127], v[140:143], v[214:217], v[124:127]
	v_mfma_f32_16x16x32_bf16 v[120:123], v[166:169], v[214:217], v[120:123]
	v_mfma_f32_16x16x32_bf16 v[108:111], v[140:143], v[222:225], v[108:111]
	v_mfma_f32_16x16x32_bf16 v[104:107], v[166:169], v[222:225], v[104:107]
	v_mfma_f32_16x16x32_bf16 v[92:95], v[140:143], v[230:233], v[92:95]
	v_mfma_f32_16x16x32_bf16 v[88:91], v[166:169], v[230:233], v[88:91]
	v_mfma_f32_16x16x32_bf16 v[76:79], v[140:143], v[238:241], v[76:79]
	v_mfma_f32_16x16x32_bf16 v[72:75], v[166:169], v[238:241], v[72:75]
	v_mfma_f32_16x16x32_bf16 v[124:127], v[162:165], v[218:221], v[124:127]
	v_mfma_f32_16x16x32_bf16 v[120:123], v[170:173], v[218:221], v[120:123]
	v_mfma_f32_16x16x32_bf16 v[108:111], v[162:165], v[226:229], v[108:111]
	v_mfma_f32_16x16x32_bf16 v[104:107], v[170:173], v[226:229], v[104:107]
	v_mfma_f32_16x16x32_bf16 v[92:95], v[162:165], v[234:237], v[92:95]
	v_mfma_f32_16x16x32_bf16 v[88:91], v[170:173], v[234:237], v[88:91]
	v_mfma_f32_16x16x32_bf16 v[76:79], v[162:165], v[242:245], v[76:79]
	v_mfma_f32_16x16x32_bf16 v[72:75], v[170:173], v[242:245], v[72:75]
	s_setprio 0
	s_setprio 1
	v_mfma_f32_16x16x32_bf16 v[116:119], v[180:183], v[214:217], v[116:119]
	v_mfma_f32_16x16x32_bf16 v[112:115], v[188:191], v[214:217], v[112:115]
	v_mfma_f32_16x16x32_bf16 v[100:103], v[180:183], v[222:225], v[100:103]
	v_mfma_f32_16x16x32_bf16 v[96:99], v[188:191], v[222:225], v[96:99]
	v_mfma_f32_16x16x32_bf16 v[84:87], v[180:183], v[230:233], v[84:87]
	v_mfma_f32_16x16x32_bf16 v[80:83], v[188:191], v[230:233], v[80:83]
	v_mfma_f32_16x16x32_bf16 v[68:71], v[180:183], v[238:241], v[68:71]
	v_mfma_f32_16x16x32_bf16 v[64:67], v[188:191], v[238:241], v[64:67]
	v_mfma_f32_16x16x32_bf16 v[116:119], v[184:187], v[218:221], v[116:119]
	v_mfma_f32_16x16x32_bf16 v[112:115], v[210:213], v[218:221], v[112:115]
	v_mfma_f32_16x16x32_bf16 v[100:103], v[184:187], v[226:229], v[100:103]
	v_mfma_f32_16x16x32_bf16 v[96:99], v[210:213], v[226:229], v[96:99]
	v_mfma_f32_16x16x32_bf16 v[84:87], v[184:187], v[234:237], v[84:87]
	v_mfma_f32_16x16x32_bf16 v[80:83], v[210:213], v[234:237], v[80:83]
	s_barrier
	v_mfma_f32_16x16x32_bf16 v[68:71], v[184:187], v[242:245], v[68:71]
	v_mfma_f32_16x16x32_bf16 v[64:67], v[210:213], v[242:245], v[64:67]
	s_setprio 0
	s_mov_b32 m0, s31
	v_lshl_add_u64 v[174:175], s[2:3], 0, v[132:133]
	s_add_u32 s56, s2, 0x40000
	ds_read_b128 v[214:217], v178 offset:16384
	ds_read_b128 v[218:221], v178 offset:17408
	ds_read_b128 v[222:225], v178 offset:18432
	ds_read_b128 v[226:229], v178 offset:19456
	ds_read_b128 v[230:233], v178 offset:20480
	ds_read_b128 v[234:237], v178 offset:21504
	ds_read_b128 v[238:241], v178 offset:22528
	ds_read_b128 v[242:245], v178 offset:23552
	global_load_lds_dwordx4 v[174:175], off
	v_lshl_add_u64 v[208:209], s[2:3], 0, v[128:129]
	s_mov_b32 m0, s34
	s_addc_u32 s57, s3, 0
	global_load_lds_dwordx4 v[208:209], off
	v_lshl_add_u64 v[246:247], s[56:57], 0, v[132:133]
	s_mov_b32 m0, s35
	v_lshl_add_u64 v[248:249], s[4:5], 0, v[130:131]
	global_load_lds_dwordx4 v[246:247], off
	v_lshl_add_u64 v[246:247], s[56:57], 0, v[128:129]
	s_mov_b32 m0, s40
	s_nop 0
	global_load_lds_dwordx4 v[246:247], off
	v_lshl_add_u64 v[246:247], s[4:5], 0, v[134:135]
	s_mov_b32 m0, s6
	s_nop 0
	global_load_lds_dwordx4 v[246:247], off
	s_mov_b32 m0, s41
	s_nop 0
	global_load_lds_dwordx4 v[248:249], off
	s_waitcnt vmcnt(8)
	s_waitcnt lgkmcnt(0)
	s_barrier
; #define PG8_STAGE(bufoff, gbase, voff) do { _Pragma("unroll") for (int _i = 0; _i < 2; ++_i) \
;         __builtin_amdgcn_global_load_lds((const unsigned*)((const char*)(gbase) + (voff)[_i]), (PG8_LAS unsigned*)(lds + (bufoff) + ldsw + _i * 8192), 16, 0, 0); } while (0)
; #define PG8_LDA(dst, b, h) do { _Pragma("unroll") for (int m = 0; m < 4; ++m) _Pragma("unroll") for (int k = 0; k < 2; ++k) dst[m][k] = *(const PG8_LAS bf16x8*)(lds + PG8_SA(b, h) + aoff + m * 2048 + k * 1024); } while (0)
; #define PG8_LDB(dst, b, h) do { _Pragma("unroll") for (int n = 0; n < 2; ++n) _Pragma("unroll") for (int k = 0; k < 2; ++k) dst[n][k] = *(const PG8_LAS bf16x8*)(lds + PG8_SB(b, h) + boff + n * 2048 + k * 1024); } while (0)
; #define PG8_MMA(ai, bj, At, Bt) do { __builtin_amdgcn_s_setprio(1); _Pragma("unroll") for (int m = 0; m < 4; ++m) _Pragma("unroll") for (int n = 0; n < 2; ++n) _Pragma("unroll") for (int k = 0; k < 2; ++k) \
;         acc[ai][bj][m][n] = __builtin_amdgcn_mfma_f32_16x16x32_bf16(Bt[n][k], At[m][k], acc[ai][bj][m][n], 0, 0, 0); __builtin_amdgcn_s_setprio(0); } while (0)
; #define PG8_WAIT_V(n) asm volatile("s_waitcnt vmcnt(" #n ")" ::: "memory")
; #define PG8_WAIT_L(n) asm volatile("s_waitcnt lgkmcnt(" #n ")" ::: "memory")
; #define PG8_BAR __builtin_amdgcn_s_barrier()
; #define PG8_SCHED __builtin_amdgcn_sched_barrier(0)
; template <class Epi, class Sched, bool ALIGN_EPI = false, bool SP2 = false>
; __device__ __forceinline__ void gemm_phase(PG8_LAS unsigned char* lds, const Gemm g, const Sched& S, const Epi& E) {
;     ...
;             PG8_WAIT_V(8); PG8_WAIT_L(0); PG8_BAR; PG8_MMA(1, 0, At, B0); PG8_MMA(1, 1, At, B1); PG8_BAR; PG8_SCHED;
;             PG8_LDB(B0, 1, 0); PG8_LDB(B1, 1, 1); PG8_SCHED; PG8_LDA(At, 1, 0); PG8_STAGE(PG8_SA(0, 1), a2 + hstep, voffA);
;             PG8_WAIT_V(8); PG8_WAIT_L(0); PG8_BAR; PG8_MMA(0, 0, At, B0); PG8_MMA(0, 1, At, B1); PG8_BAR; PG8_SCHED;
	s_setprio 1
	s_waitcnt lgkmcnt(0)
	v_mfma_f32_16x16x32_bf16 v[60:63], v[140:143], v[214:217], v[60:63]
	v_mfma_f32_16x16x32_bf16 v[56:59], v[166:169], v[214:217], v[56:59]
	v_mfma_f32_16x16x32_bf16 v[44:47], v[140:143], v[222:225], v[44:47]
	v_mfma_f32_16x16x32_bf16 v[40:43], v[166:169], v[222:225], v[40:43]
	v_mfma_f32_16x16x32_bf16 v[28:31], v[140:143], v[230:233], v[28:31]
	v_mfma_f32_16x16x32_bf16 v[24:27], v[166:169], v[230:233], v[24:27]
	v_mfma_f32_16x16x32_bf16 v[12:15], v[140:143], v[238:241], v[12:15]
	v_mfma_f32_16x16x32_bf16 v[8:11], v[166:169], v[238:241], v[8:11]
	v_mfma_f32_16x16x32_bf16 v[60:63], v[162:165], v[218:221], v[60:63]
	v_mfma_f32_16x16x32_bf16 v[56:59], v[170:173], v[218:221], v[56:59]
	v_mfma_f32_16x16x32_bf16 v[44:47], v[162:165], v[226:229], v[44:47]
	v_mfma_f32_16x16x32_bf16 v[40:43], v[170:173], v[226:229], v[40:43]
	v_mfma_f32_16x16x32_bf16 v[28:31], v[162:165], v[234:237], v[28:31]
	v_mfma_f32_16x16x32_bf16 v[24:27], v[170:173], v[234:237], v[24:27]
	v_mfma_f32_16x16x32_bf16 v[12:15], v[162:165], v[242:245], v[12:15]
	v_mfma_f32_16x16x32_bf16 v[8:11], v[170:173], v[242:245], v[8:11]
	s_setprio 0
	s_setprio 1
	v_mfma_f32_16x16x32_bf16 v[52:55], v[180:183], v[214:217], v[52:55]
	v_mfma_f32_16x16x32_bf16 v[48:51], v[188:191], v[214:217], v[48:51]
	v_mfma_f32_16x16x32_bf16 v[36:39], v[180:183], v[222:225], v[36:39]
	v_mfma_f32_16x16x32_bf16 v[32:35], v[188:191], v[222:225], v[32:35]
	v_mfma_f32_16x16x32_bf16 v[20:23], v[180:183], v[230:233], v[20:23]
	v_mfma_f32_16x16x32_bf16 v[16:19], v[188:191], v[230:233], v[16:19]
	v_mfma_f32_16x16x32_bf16 v[4:7], v[180:183], v[238:241], v[4:7]
	v_mfma_f32_16x16x32_bf16 v[0:3], v[188:191], v[238:241], v[0:3]
	v_mfma_f32_16x16x32_bf16 v[52:55], v[184:187], v[218:221], v[52:55]
	v_mfma_f32_16x16x32_bf16 v[48:51], v[210:213], v[218:221], v[48:51]
	v_mfma_f32_16x16x32_bf16 v[36:39], v[184:187], v[226:229], v[36:39]
	v_mfma_f32_16x16x32_bf16 v[32:35], v[210:213], v[226:229], v[32:35]
	v_mfma_f32_16x16x32_bf16 v[20:23], v[184:187], v[234:237], v[20:23]
	v_mfma_f32_16x16x32_bf16 v[16:19], v[210:213], v[234:237], v[16:19]
	s_barrier
	v_mfma_f32_16x16x32_bf16 v[4:7], v[184:187], v[242:245], v[4:7]
	v_mfma_f32_16x16x32_bf16 v[0:3], v[210:213], v[242:245], v[0:3]
	s_setprio 0
	v_or_b32_e32 v140, 0x18000, v179
	v_add_u32_e32 v147, 0x18400, v179
	ds_read_b128 v[140:143], v140
	ds_read_b128 v[162:165], v147
	v_add_u32_e32 v147, 0x18800, v179
	v_add_u32_e32 v170, 0x18c00, v179
	ds_read_b128 v[166:169], v147
	ds_read_b128 v[170:173], v170
	v_or_b32_e32 v147, 0x1c000, v179
	v_add_u32_e32 v184, 0x1c400, v179
	ds_read_b128 v[180:183], v147
	ds_read_b128 v[184:187], v184
	v_add_u32_e32 v147, 0x1c800, v179
	v_add_u32_e32 v210, 0x1cc00, v179
	ds_read_b128 v[188:191], v147
	ds_read_b128 v[210:213], v210
	s_add_u32 s4, s4, 0x40000
	s_addc_u32 s5, s5, 0
	s_mov_b32 m0, s42
	v_lshl_add_u64 v[250:251], s[4:5], 0, v[134:135]
	ds_read_b128 v[214:217], v178 offset:32768
	ds_read_b128 v[218:221], v178 offset:33792
	ds_read_b128 v[222:225], v178 offset:34816
	ds_read_b128 v[226:229], v178 offset:35840
	ds_read_b128 v[230:233], v178 offset:36864
	ds_read_b128 v[234:237], v178 offset:37888
	ds_read_b128 v[238:241], v178 offset:38912
	ds_read_b128 v[242:245], v178 offset:39936
	global_load_lds_dwordx4 v[250:251], off
	v_lshl_add_u64 v[250:251], s[4:5], 0, v[130:131]
	s_mov_b32 m0, s43
	s_nop 0
	global_load_lds_dwordx4 v[250:251], off
	s_waitcnt vmcnt(8)
	s_waitcnt lgkmcnt(0)
	s_barrier
	s_setprio 1
	s_waitcnt lgkmcnt(0)
	v_mfma_f32_16x16x32_bf16 v[124:127], v[140:143], v[214:217], v[124:127]
	v_mfma_f32_16x16x32_bf16 v[120:123], v[166:169], v[214:217], v[120:123]
	v_mfma_f32_16x16x32_bf16 v[108:111], v[140:143], v[222:225], v[108:111]
	v_mfma_f32_16x16x32_bf16 v[104:107], v[166:169], v[222:225], v[104:107]
	v_mfma_f32_16x16x32_bf16 v[92:95], v[140:143], v[230:233], v[92:95]
	v_mfma_f32_16x16x32_bf16 v[88:91], v[166:169], v[230:233], v[88:91]
	v_mfma_f32_16x16x32_bf16 v[76:79], v[140:143], v[238:241], v[76:79]
	v_mfma_f32_16x16x32_bf16 v[72:75], v[166:169], v[238:241], v[72:75]
	v_mfma_f32_16x16x32_bf16 v[124:127], v[162:165], v[218:221], v[124:127]
	v_mfma_f32_16x16x32_bf16 v[120:123], v[170:173], v[218:221], v[120:123]
	v_mfma_f32_16x16x32_bf16 v[108:111], v[162:165], v[226:229], v[108:111]
	v_mfma_f32_16x16x32_bf16 v[104:107], v[170:173], v[226:229], v[104:107]
	v_mfma_f32_16x16x32_bf16 v[92:95], v[162:165], v[234:237], v[92:95]
	v_mfma_f32_16x16x32_bf16 v[88:91], v[170:173], v[234:237], v[88:91]
	v_mfma_f32_16x16x32_bf16 v[76:79], v[162:165], v[242:245], v[76:79]
	v_mfma_f32_16x16x32_bf16 v[72:75], v[170:173], v[242:245], v[72:75]
	s_setprio 0
	s_setprio 1
	v_mfma_f32_16x16x32_bf16 v[116:119], v[180:183], v[214:217], v[116:119]
	v_mfma_f32_16x16x32_bf16 v[112:115], v[188:191], v[214:217], v[112:115]
	v_mfma_f32_16x16x32_bf16 v[100:103], v[180:183], v[222:225], v[100:103]
	v_mfma_f32_16x16x32_bf16 v[96:99], v[188:191], v[222:225], v[96:99]
	v_mfma_f32_16x16x32_bf16 v[84:87], v[180:183], v[230:233], v[84:87]
	v_mfma_f32_16x16x32_bf16 v[80:83], v[188:191], v[230:233], v[80:83]
	v_mfma_f32_16x16x32_bf16 v[68:71], v[180:183], v[238:241], v[68:71]
	v_mfma_f32_16x16x32_bf16 v[64:67], v[188:191], v[238:241], v[64:67]
	v_mfma_f32_16x16x32_bf16 v[116:119], v[184:187], v[218:221], v[116:119]
	v_mfma_f32_16x16x32_bf16 v[112:115], v[210:213], v[218:221], v[112:115]
	v_mfma_f32_16x16x32_bf16 v[100:103], v[184:187], v[226:229], v[100:103]
	v_mfma_f32_16x16x32_bf16 v[96:99], v[210:213], v[226:229], v[96:99]
	v_mfma_f32_16x16x32_bf16 v[84:87], v[184:187], v[234:237], v[84:87]
	v_mfma_f32_16x16x32_bf16 v[80:83], v[210:213], v[234:237], v[80:83]
	s_barrier
; #define PG8_STAGE(bufoff, gbase, voff) do { _Pragma("unroll") for (int _i = 0; _i < 2; ++_i) \
;         __builtin_amdgcn_global_load_lds((const unsigned*)((const char*)(gbase) + (voff)[_i]), (PG8_LAS unsigned*)(lds + (bufoff) + ldsw + _i * 8192), 16, 0, 0); } while (0)
; #define PG8_LDA(dst, b, h) do { _Pragma("unroll") for (int m = 0; m < 4; ++m) _Pragma("unroll") for (int k = 0; k < 2; ++k) dst[m][k] = *(const PG8_LAS bf16x8*)(lds + PG8_SA(b, h) + aoff + m * 2048 + k * 1024); } while (0)
; #define PG8_MMA(ai, bj, At, Bt) do { __builtin_amdgcn_s_setprio(1); _Pragma("unroll") for (int m = 0; m < 4; ++m) _Pragma("unroll") for (int n = 0; n < 2; ++n) _Pragma("unroll") for (int k = 0; k < 2; ++k) \
;         acc[ai][bj][m][n] = __builtin_amdgcn_mfma_f32_16x16x32_bf16(Bt[n][k], At[m][k], acc[ai][bj][m][n], 0, 0, 0); __builtin_amdgcn_s_setprio(0); } while (0)
; #define PG8_WAIT_V(n) asm volatile("s_waitcnt vmcnt(" #n ")" ::: "memory")
; #define PG8_WAIT_L(n) asm volatile("s_waitcnt lgkmcnt(" #n ")" ::: "memory")
; #define PG8_BAR __builtin_amdgcn_s_barrier()
; #define PG8_SCHED __builtin_amdgcn_sched_barrier(0)
; template <class Epi, class Sched, bool ALIGN_EPI = false, bool SP2 = false>
; __device__ __forceinline__ void gemm_phase(PG8_LAS unsigned char* lds, const Gemm g, const Sched& S, const Epi& E) {
;     ...
;             PG8_WAIT_V(8); PG8_WAIT_L(0); PG8_BAR; PG8_MMA(0, 0, At, B0); PG8_MMA(0, 1, At, B1); PG8_BAR; PG8_SCHED;
;             PG8_LDA(At, 1, 1); PG8_STAGE(PG8_SB(1, 0), b3, voffB); PG8_STAGE(PG8_SB(1, 1), b3 + hstep, voffB); PG8_STAGE(PG8_SA(1, 0), a3, voffA);
;             PG8_WAIT_V(8); PG8_WAIT_L(0); PG8_BAR; PG8_MMA(1, 0, At, B0); PG8_MMA(1, 1, At, B1); PG8_BAR; PG8_SCHED;
	v_mfma_f32_16x16x32_bf16 v[68:71], v[184:187], v[242:245], v[68:71]
	v_mfma_f32_16x16x32_bf16 v[64:67], v[210:213], v[242:245], v[64:67]
	s_setprio 0
	s_mov_b32 m0, s48
	v_lshl_add_u64 v[174:175], v[174:175], 0, s[94:95]
	s_add_u32 s2, s2, 0x40080
	ds_read_b128 v[214:217], v178 offset:49152
	ds_read_b128 v[218:221], v178 offset:50176
	ds_read_b128 v[222:225], v178 offset:51200
	ds_read_b128 v[226:229], v178 offset:52224
	ds_read_b128 v[230:233], v178 offset:53248
	ds_read_b128 v[234:237], v178 offset:54272
	ds_read_b128 v[238:241], v178 offset:55296
	ds_read_b128 v[242:245], v178 offset:56320
	global_load_lds_dwordx4 v[174:175], off
	v_lshl_add_u64 v[174:175], v[208:209], 0, s[94:95]
	s_mov_b32 m0, s49
	s_addc_u32 s3, s3, 0
	global_load_lds_dwordx4 v[174:175], off
	v_lshl_add_u64 v[174:175], s[2:3], 0, v[132:133]
	s_mov_b32 m0, s52
	s_nop 0
	global_load_lds_dwordx4 v[174:175], off
	v_lshl_add_u64 v[174:175], s[2:3], 0, v[128:129]
	s_mov_b32 m0, s53
	s_nop 0
	global_load_lds_dwordx4 v[174:175], off
	v_lshl_add_u64 v[174:175], v[246:247], 0, s[94:95]
	s_mov_b32 m0, s50
	s_nop 0
	global_load_lds_dwordx4 v[174:175], off
	v_lshl_add_u64 v[174:175], v[248:249], 0, s[94:95]
	s_mov_b32 m0, s51
	s_nop 0
	global_load_lds_dwordx4 v[174:175], off
	s_waitcnt vmcnt(8)
	s_waitcnt lgkmcnt(0)
	s_barrier
	s_setprio 1
	s_waitcnt lgkmcnt(0)
	v_mfma_f32_16x16x32_bf16 v[60:63], v[140:143], v[214:217], v[60:63]
	v_mfma_f32_16x16x32_bf16 v[56:59], v[166:169], v[214:217], v[56:59]
	v_mfma_f32_16x16x32_bf16 v[44:47], v[140:143], v[222:225], v[44:47]
	v_mfma_f32_16x16x32_bf16 v[40:43], v[166:169], v[222:225], v[40:43]
	v_mfma_f32_16x16x32_bf16 v[28:31], v[140:143], v[230:233], v[28:31]
	v_mfma_f32_16x16x32_bf16 v[24:27], v[166:169], v[230:233], v[24:27]
	v_mfma_f32_16x16x32_bf16 v[12:15], v[140:143], v[238:241], v[12:15]
	v_mfma_f32_16x16x32_bf16 v[8:11], v[166:169], v[238:241], v[8:11]
	v_mfma_f32_16x16x32_bf16 v[60:63], v[162:165], v[218:221], v[60:63]
	v_mfma_f32_16x16x32_bf16 v[56:59], v[170:173], v[218:221], v[56:59]
	v_mfma_f32_16x16x32_bf16 v[44:47], v[162:165], v[226:229], v[44:47]
	v_mfma_f32_16x16x32_bf16 v[40:43], v[170:173], v[226:229], v[40:43]
	v_mfma_f32_16x16x32_bf16 v[28:31], v[162:165], v[234:237], v[28:31]
	v_mfma_f32_16x16x32_bf16 v[24:27], v[170:173], v[234:237], v[24:27]
	v_mfma_f32_16x16x32_bf16 v[12:15], v[162:165], v[242:245], v[12:15]
	v_mfma_f32_16x16x32_bf16 v[8:11], v[170:173], v[242:245], v[8:11]
	s_setprio 0
	s_setprio 1
	v_mfma_f32_16x16x32_bf16 v[52:55], v[180:183], v[214:217], v[52:55]
	v_mfma_f32_16x16x32_bf16 v[48:51], v[188:191], v[214:217], v[48:51]
	v_mfma_f32_16x16x32_bf16 v[36:39], v[180:183], v[222:225], v[36:39]
	v_mfma_f32_16x16x32_bf16 v[32:35], v[188:191], v[222:225], v[32:35]
	v_mfma_f32_16x16x32_bf16 v[20:23], v[180:183], v[230:233], v[20:23]
	v_mfma_f32_16x16x32_bf16 v[16:19], v[188:191], v[230:233], v[16:19]
	v_mfma_f32_16x16x32_bf16 v[4:7], v[180:183], v[238:241], v[4:7]
	v_mfma_f32_16x16x32_bf16 v[0:3], v[188:191], v[238:241], v[0:3]
	v_mfma_f32_16x16x32_bf16 v[52:55], v[184:187], v[218:221], v[52:55]
	v_mfma_f32_16x16x32_bf16 v[48:51], v[210:213], v[218:221], v[48:51]
	v_mfma_f32_16x16x32_bf16 v[36:39], v[184:187], v[226:229], v[36:39]
	v_mfma_f32_16x16x32_bf16 v[32:35], v[210:213], v[226:229], v[32:35]
	v_mfma_f32_16x16x32_bf16 v[20:23], v[184:187], v[234:237], v[20:23]
	v_mfma_f32_16x16x32_bf16 v[16:19], v[210:213], v[234:237], v[16:19]
	s_barrier
	v_mfma_f32_16x16x32_bf16 v[4:7], v[184:187], v[242:245], v[4:7]
	v_mfma_f32_16x16x32_bf16 v[0:3], v[210:213], v[242:245], v[0:3]
	s_setprio 0
	s_add_i32 s55, s55, 2
	s_add_u32 s0, s0, 0x100
	s_addc_u32 s1, s1, 0
	s_add_u32 s38, s38, 0x100
	s_addc_u32 s39, s39, 0
	s_cmp_gt_u32 s55, 13
	s_cbranch_scc0 .LBB0_749
	s_and_b64 vcc, exec, s[18:19]
	s_cbranch_vccz .LBB0_752
	s_barrier

; #define PG8_STAGE(bufoff, gbase, voff) do { _Pragma("unroll") for (int _i = 0; _i < 2; ++_i) \
;         __builtin_amdgcn_global_load_lds((const unsigned*)((const char*)(gbase) + (voff)[_i]), (PG8_LAS unsigned*)(lds + (bufoff) + ldsw + _i * 8192), 16, 0, 0); } while (0)
; #define PG8_LDA(dst, b, h) do { _Pragma("unroll") for (int m = 0; m < 4; ++m) _Pragma("unroll") for (int k = 0; k < 2; ++k) dst[m][k] = *(const PG8_LAS bf16x8*)(lds + PG8_SA(b, h) + aoff + m * 2048 + k * 1024); } while (0)
; #define PG8_LDB(dst, b, h) do { _Pragma("unroll") for (int n = 0; n < 2; ++n) _Pragma("unroll") for (int k = 0; k < 2; ++k) dst[n][k] = *(const PG8_LAS bf16x8*)(lds + PG8_SB(b, h) + boff + n * 2048 + k * 1024); } while (0)
; #define PG8_MMA(ai, bj, At, Bt) do { __builtin_amdgcn_s_setprio(1); _Pragma("unroll") for (int m = 0; m < 4; ++m) _Pragma("unroll") for (int n = 0; n < 2; ++n) _Pragma("unroll") for (int k = 0; k < 2; ++k) \
;         acc[ai][bj][m][n] = __builtin_amdgcn_mfma_f32_16x16x32_bf16(Bt[n][k], At[m][k], acc[ai][bj][m][n], 0, 0, 0); __builtin_amdgcn_s_setprio(0); } while (0)
; #define PG8_WAIT_V(n) asm volatile("s_waitcnt vmcnt(" #n ")" ::: "memory")
; #define PG8_WAIT_L(n) asm volatile("s_waitcnt lgkmcnt(" #n ")" ::: "memory")
; #define PG8_BAR __builtin_amdgcn_s_barrier()
; #define PG8_SCHED __builtin_amdgcn_sched_barrier(0)
; template <class Epi, class Sched, bool ALIGN_EPI = false, bool SP2 = false>
; __device__ __forceinline__ void gemm_phase(PG8_LAS unsigned char* lds, const Gemm g, const Sched& S, const Epi& E) {
;     ...
;             const bool last = (t == nt - 2);
;             const char* a1 = cA + (size_t)(t + 1) * kstep;
;             const char* a2 = last ? nA : cA + (size_t)(t + 2) * kstep; const char* b2 = last ? nB : cB + (size_t)(t + 2) * kstep;
;             const char* a3 = a2 + kstep; const char* b3 = b2 + kstep;
;             if (last && has_next) S.a_ready(nxt);
;             if constexpr (SP2) {
;             PG8_LDB(B0, 0, 0); PG8_LDB(B1, 0, 1); PG8_SCHED; PG8_LDA(At, 0, 0); PG8_STAGE(PG8_SA(1, 1), a1 + hstep, voffA);
;             PG8_WAIT_V(8); PG8_WAIT_L(0); PG8_BAR; PG8_MMA(0, 0, At, B0); PG8_MMA(0, 1, At, B1); PG8_BAR; PG8_SCHED;
;             PG8_LDA(At, 0, 1); PG8_STAGE(PG8_SB(0, 0), b2, voffB); PG8_STAGE(PG8_SB(0, 1), b2 + hstep, voffB); PG8_STAGE(PG8_SA(0, 0), a2, voffA);
.LBB0_792:
	s_waitcnt lgkmcnt(0)
	v_or_b32_e32 v140, 0x10000, v174
	v_add_u32_e32 v162, 0x10400, v174
	v_add_u32_e32 v166, 0x10800, v174
	v_add_u32_e32 v170, 0x10c00, v174
	ds_read_b128 v[140:143], v140
	ds_read_b128 v[162:165], v162
	ds_read_b128 v[166:169], v166
	ds_read_b128 v[176:179], v170
	v_or_b32_e32 v170, 0x14000, v174
	v_add_u32_e32 v171, 0x14400, v174
	ds_read_b128 v[180:183], v170
	ds_read_b128 v[184:187], v171
	v_add_u32_e32 v170, 0x14800, v174
	v_add_u32_e32 v171, 0x14c00, v174
	ds_read_b128 v[188:191], v170
	ds_read_b128 v[210:213], v171
	s_add_u32 s2, s0, 0xfffc0080
	s_addc_u32 s3, s1, -1
	s_cmp_eq_u32 s52, 12
	s_cselect_b32 s5, s17, s3
	s_cselect_b32 s4, s48, s2
	s_cselect_b32 s3, s15, s51
	s_cselect_b32 s2, s49, s50
	v_lshl_add_u64 v[170:171], s[0:1], 0, v[136:137]
	s_add_i32 m0, s6, 0xc000
	ds_read_b128 v[214:217], v173
	ds_read_b128 v[218:221], v173 offset:1024
	ds_read_b128 v[222:225], v173 offset:2048
	ds_read_b128 v[226:229], v173 offset:3072
	ds_read_b128 v[230:233], v173 offset:4096
	ds_read_b128 v[234:237], v173 offset:5120
	ds_read_b128 v[238:241], v173 offset:6144
	ds_read_b128 v[242:245], v173 offset:7168
	global_load_lds_dwordx4 v[170:171], off
	v_lshl_add_u64 v[170:171], s[0:1], 0, v[138:139]
	s_add_i32 m0, s6, 0xe000
	s_nop 0
	global_load_lds_dwordx4 v[170:171], off
	s_waitcnt vmcnt(8)
	s_waitcnt lgkmcnt(0)
	s_barrier
	s_setprio 1
	s_waitcnt lgkmcnt(0)
	v_mfma_f32_16x16x32_bf16 v[124:127], v[140:143], v[214:217], v[124:127]
	v_mfma_f32_16x16x32_bf16 v[120:123], v[166:169], v[214:217], v[120:123]
	v_mfma_f32_16x16x32_bf16 v[112:115], v[140:143], v[222:225], v[112:115]
	v_mfma_f32_16x16x32_bf16 v[104:107], v[166:169], v[222:225], v[104:107]
	v_mfma_f32_16x16x32_bf16 v[96:99], v[140:143], v[230:233], v[96:99]
	v_mfma_f32_16x16x32_bf16 v[88:91], v[166:169], v[230:233], v[88:91]
	v_mfma_f32_16x16x32_bf16 v[80:83], v[140:143], v[238:241], v[80:83]
	v_mfma_f32_16x16x32_bf16 v[72:75], v[166:169], v[238:241], v[72:75]
	v_mfma_f32_16x16x32_bf16 v[124:127], v[162:165], v[218:221], v[124:127]
	v_mfma_f32_16x16x32_bf16 v[120:123], v[176:179], v[218:221], v[120:123]
	v_mfma_f32_16x16x32_bf16 v[112:115], v[162:165], v[226:229], v[112:115]
	v_mfma_f32_16x16x32_bf16 v[104:107], v[176:179], v[226:229], v[104:107]
	v_mfma_f32_16x16x32_bf16 v[96:99], v[162:165], v[234:237], v[96:99]
	v_mfma_f32_16x16x32_bf16 v[88:91], v[176:179], v[234:237], v[88:91]
	v_mfma_f32_16x16x32_bf16 v[80:83], v[162:165], v[242:245], v[80:83]
	v_mfma_f32_16x16x32_bf16 v[72:75], v[176:179], v[242:245], v[72:75]
	s_setprio 0
	s_setprio 1
	v_mfma_f32_16x16x32_bf16 v[116:119], v[180:183], v[214:217], v[116:119]
	v_mfma_f32_16x16x32_bf16 v[108:111], v[188:191], v[214:217], v[108:111]
	v_mfma_f32_16x16x32_bf16 v[100:103], v[180:183], v[222:225], v[100:103]
	v_mfma_f32_16x16x32_bf16 v[92:95], v[188:191], v[222:225], v[92:95]
	v_mfma_f32_16x16x32_bf16 v[84:87], v[180:183], v[230:233], v[84:87]
	v_mfma_f32_16x16x32_bf16 v[76:79], v[188:191], v[230:233], v[76:79]
	v_mfma_f32_16x16x32_bf16 v[68:71], v[180:183], v[238:241], v[68:71]
	v_mfma_f32_16x16x32_bf16 v[64:67], v[188:191], v[238:241], v[64:67]
	v_mfma_f32_16x16x32_bf16 v[116:119], v[184:187], v[218:221], v[116:119]
	v_mfma_f32_16x16x32_bf16 v[108:111], v[210:213], v[218:221], v[108:111]
	v_mfma_f32_16x16x32_bf16 v[100:103], v[184:187], v[226:229], v[100:103]
	v_mfma_f32_16x16x32_bf16 v[92:95], v[210:213], v[226:229], v[92:95]
	v_mfma_f32_16x16x32_bf16 v[84:87], v[184:187], v[234:237], v[84:87]
	v_mfma_f32_16x16x32_bf16 v[76:79], v[210:213], v[234:237], v[76:79]
	s_barrier
	v_mfma_f32_16x16x32_bf16 v[68:71], v[184:187], v[242:245], v[68:71]
	v_mfma_f32_16x16x32_bf16 v[64:67], v[210:213], v[242:245], v[64:67]
	s_setprio 0
	s_mov_b32 m0, s27
	v_lshl_add_u64 v[170:171], s[2:3], 0, v[132:133]
	s_add_u32 s54, s2, 0x40000
	ds_read_b128 v[214:217], v173 offset:16384
	ds_read_b128 v[218:221], v173 offset:17408
	ds_read_b128 v[222:225], v173 offset:18432
	ds_read_b128 v[226:229], v173 offset:19456
	ds_read_b128 v[230:233], v173 offset:20480
	ds_read_b128 v[234:237], v173 offset:21504
	ds_read_b128 v[238:241], v173 offset:22528
	ds_read_b128 v[242:245], v173 offset:23552
	global_load_lds_dwordx4 v[170:171], off
	v_lshl_add_u64 v[208:209], s[2:3], 0, v[128:129]
	s_mov_b32 m0, s28
	s_addc_u32 s55, s3, 0
	global_load_lds_dwordx4 v[208:209], off
	v_lshl_add_u64 v[246:247], s[54:55], 0, v[132:133]
	s_mov_b32 m0, s29
	v_lshl_add_u64 v[248:249], s[4:5], 0, v[130:131]
	global_load_lds_dwordx4 v[246:247], off
	v_lshl_add_u64 v[246:247], s[54:55], 0, v[128:129]
	s_mov_b32 m0, s30
	s_nop 0
	global_load_lds_dwordx4 v[246:247], off
	v_lshl_add_u64 v[246:247], s[4:5], 0, v[134:135]
	s_mov_b32 m0, s6
	s_nop 0
	global_load_lds_dwordx4 v[246:247], off
	s_mov_b32 m0, s31
	s_nop 0
	global_load_lds_dwordx4 v[248:249], off
	s_waitcnt vmcnt(8)
	s_waitcnt lgkmcnt(0)
	s_barrier
; #define PG8_STAGE(bufoff, gbase, voff) do { _Pragma("unroll") for (int _i = 0; _i < 2; ++_i) \
;         __builtin_amdgcn_global_load_lds((const unsigned*)((const char*)(gbase) + (voff)[_i]), (PG8_LAS unsigned*)(lds + (bufoff) + ldsw + _i * 8192), 16, 0, 0); } while (0)
; #define PG8_LDA(dst, b, h) do { _Pragma("unroll") for (int m = 0; m < 4; ++m) _Pragma("unroll") for (int k = 0; k < 2; ++k) dst[m][k] = *(const PG8_LAS bf16x8*)(lds + PG8_SA(b, h) + aoff + m * 2048 + k * 1024); } while (0)
; #define PG8_LDB(dst, b, h) do { _Pragma("unroll") for (int n = 0; n < 2; ++n) _Pragma("unroll") for (int k = 0; k < 2; ++k) dst[n][k] = *(const PG8_LAS bf16x8*)(lds + PG8_SB(b, h) + boff + n * 2048 + k * 1024); } while (0)
; #define PG8_MMA(ai, bj, At, Bt) do { __builtin_amdgcn_s_setprio(1); _Pragma("unroll") for (int m = 0; m < 4; ++m) _Pragma("unroll") for (int n = 0; n < 2; ++n) _Pragma("unroll") for (int k = 0; k < 2; ++k) \
;         acc[ai][bj][m][n] = __builtin_amdgcn_mfma_f32_16x16x32_bf16(Bt[n][k], At[m][k], acc[ai][bj][m][n], 0, 0, 0); __builtin_amdgcn_s_setprio(0); } while (0)
; #define PG8_WAIT_V(n) asm volatile("s_waitcnt vmcnt(" #n ")" ::: "memory")
; #define PG8_WAIT_L(n) asm volatile("s_waitcnt lgkmcnt(" #n ")" ::: "memory")
; #define PG8_BAR __builtin_amdgcn_s_barrier()
; #define PG8_SCHED __builtin_amdgcn_sched_barrier(0)
; template <class Epi, class Sched, bool ALIGN_EPI = false, bool SP2 = false>
; __device__ __forceinline__ void gemm_phase(PG8_LAS unsigned char* lds, const Gemm g, const Sched& S, const Epi& E) {
;     ...
;             PG8_WAIT_V(8); PG8_WAIT_L(0); PG8_BAR; PG8_MMA(1, 0, At, B0); PG8_MMA(1, 1, At, B1); PG8_BAR; PG8_SCHED;
;             PG8_LDB(B0, 1, 0); PG8_LDB(B1, 1, 1); PG8_SCHED; PG8_LDA(At, 1, 0); PG8_STAGE(PG8_SA(0, 1), a2 + hstep, voffA);
;             PG8_WAIT_V(8); PG8_WAIT_L(0); PG8_BAR; PG8_MMA(0, 0, At, B0); PG8_MMA(0, 1, At, B1); PG8_BAR; PG8_SCHED;
	s_setprio 1
	s_waitcnt lgkmcnt(0)
	v_mfma_f32_16x16x32_bf16 v[60:63], v[140:143], v[214:217], v[60:63]
	v_mfma_f32_16x16x32_bf16 v[56:59], v[166:169], v[214:217], v[56:59]
	v_mfma_f32_16x16x32_bf16 v[48:51], v[140:143], v[222:225], v[48:51]
	v_mfma_f32_16x16x32_bf16 v[40:43], v[166:169], v[222:225], v[40:43]
	v_mfma_f32_16x16x32_bf16 v[32:35], v[140:143], v[230:233], v[32:35]
	v_mfma_f32_16x16x32_bf16 v[24:27], v[166:169], v[230:233], v[24:27]
	v_mfma_f32_16x16x32_bf16 v[16:19], v[140:143], v[238:241], v[16:19]
	v_mfma_f32_16x16x32_bf16 v[8:11], v[166:169], v[238:241], v[8:11]
	v_mfma_f32_16x16x32_bf16 v[60:63], v[162:165], v[218:221], v[60:63]
	v_mfma_f32_16x16x32_bf16 v[56:59], v[176:179], v[218:221], v[56:59]
	v_mfma_f32_16x16x32_bf16 v[48:51], v[162:165], v[226:229], v[48:51]
	v_mfma_f32_16x16x32_bf16 v[40:43], v[176:179], v[226:229], v[40:43]
	v_mfma_f32_16x16x32_bf16 v[32:35], v[162:165], v[234:237], v[32:35]
	v_mfma_f32_16x16x32_bf16 v[24:27], v[176:179], v[234:237], v[24:27]
	v_mfma_f32_16x16x32_bf16 v[16:19], v[162:165], v[242:245], v[16:19]
	v_mfma_f32_16x16x32_bf16 v[8:11], v[176:179], v[242:245], v[8:11]
	s_setprio 0
	s_setprio 1
	v_mfma_f32_16x16x32_bf16 v[52:55], v[180:183], v[214:217], v[52:55]
	v_mfma_f32_16x16x32_bf16 v[44:47], v[188:191], v[214:217], v[44:47]
	v_mfma_f32_16x16x32_bf16 v[36:39], v[180:183], v[222:225], v[36:39]
	v_mfma_f32_16x16x32_bf16 v[28:31], v[188:191], v[222:225], v[28:31]
	v_mfma_f32_16x16x32_bf16 v[20:23], v[180:183], v[230:233], v[20:23]
	v_mfma_f32_16x16x32_bf16 v[12:15], v[188:191], v[230:233], v[12:15]
	v_mfma_f32_16x16x32_bf16 v[4:7], v[180:183], v[238:241], v[4:7]
	v_mfma_f32_16x16x32_bf16 v[0:3], v[188:191], v[238:241], v[0:3]
	v_mfma_f32_16x16x32_bf16 v[52:55], v[184:187], v[218:221], v[52:55]
	v_mfma_f32_16x16x32_bf16 v[44:47], v[210:213], v[218:221], v[44:47]
	v_mfma_f32_16x16x32_bf16 v[36:39], v[184:187], v[226:229], v[36:39]
	v_mfma_f32_16x16x32_bf16 v[28:31], v[210:213], v[226:229], v[28:31]
	v_mfma_f32_16x16x32_bf16 v[20:23], v[184:187], v[234:237], v[20:23]
	v_mfma_f32_16x16x32_bf16 v[12:15], v[210:213], v[234:237], v[12:15]
	s_barrier
	v_mfma_f32_16x16x32_bf16 v[4:7], v[184:187], v[242:245], v[4:7]
	v_mfma_f32_16x16x32_bf16 v[0:3], v[210:213], v[242:245], v[0:3]
	s_setprio 0
	v_or_b32_e32 v140, 0x18000, v174
	v_add_u32_e32 v162, 0x18400, v174
	v_add_u32_e32 v166, 0x18800, v174
	v_add_u32_e32 v175, 0x18c00, v174
	ds_read_b128 v[140:143], v140
	ds_read_b128 v[162:165], v162
	ds_read_b128 v[166:169], v166
	ds_read_b128 v[176:179], v175
	v_or_b32_e32 v175, 0x1c000, v174
	v_add_u32_e32 v184, 0x1c400, v174
	ds_read_b128 v[180:183], v175
	ds_read_b128 v[184:187], v184
	v_add_u32_e32 v175, 0x1c800, v174
	v_add_u32_e32 v210, 0x1cc00, v174
	ds_read_b128 v[188:191], v175
	ds_read_b128 v[210:213], v210
	s_add_u32 s4, s4, 0x40000
	s_addc_u32 s5, s5, 0
	s_mov_b32 m0, s33
	v_lshl_add_u64 v[250:251], s[4:5], 0, v[134:135]
	ds_read_b128 v[214:217], v173 offset:32768
	ds_read_b128 v[218:221], v173 offset:33792
	ds_read_b128 v[222:225], v173 offset:34816
	ds_read_b128 v[226:229], v173 offset:35840
	ds_read_b128 v[230:233], v173 offset:36864
	ds_read_b128 v[234:237], v173 offset:37888
	ds_read_b128 v[238:241], v173 offset:38912
	ds_read_b128 v[242:245], v173 offset:39936
	global_load_lds_dwordx4 v[250:251], off
	v_lshl_add_u64 v[250:251], s[4:5], 0, v[130:131]
	s_mov_b32 m0, s34
	s_nop 0
	global_load_lds_dwordx4 v[250:251], off
	s_waitcnt vmcnt(8)
	s_waitcnt lgkmcnt(0)
	s_barrier
	s_setprio 1
	s_waitcnt lgkmcnt(0)
	v_mfma_f32_16x16x32_bf16 v[124:127], v[140:143], v[214:217], v[124:127]
	v_mfma_f32_16x16x32_bf16 v[120:123], v[166:169], v[214:217], v[120:123]
	v_mfma_f32_16x16x32_bf16 v[112:115], v[140:143], v[222:225], v[112:115]
	v_mfma_f32_16x16x32_bf16 v[104:107], v[166:169], v[222:225], v[104:107]
	v_mfma_f32_16x16x32_bf16 v[96:99], v[140:143], v[230:233], v[96:99]
	v_mfma_f32_16x16x32_bf16 v[88:91], v[166:169], v[230:233], v[88:91]
	v_mfma_f32_16x16x32_bf16 v[80:83], v[140:143], v[238:241], v[80:83]
	v_mfma_f32_16x16x32_bf16 v[72:75], v[166:169], v[238:241], v[72:75]
	v_mfma_f32_16x16x32_bf16 v[124:127], v[162:165], v[218:221], v[124:127]
	v_mfma_f32_16x16x32_bf16 v[120:123], v[176:179], v[218:221], v[120:123]
	v_mfma_f32_16x16x32_bf16 v[112:115], v[162:165], v[226:229], v[112:115]
	v_mfma_f32_16x16x32_bf16 v[104:107], v[176:179], v[226:229], v[104:107]
	v_mfma_f32_16x16x32_bf16 v[96:99], v[162:165], v[234:237], v[96:99]
	v_mfma_f32_16x16x32_bf16 v[88:91], v[176:179], v[234:237], v[88:91]
	v_mfma_f32_16x16x32_bf16 v[80:83], v[162:165], v[242:245], v[80:83]
	v_mfma_f32_16x16x32_bf16 v[72:75], v[176:179], v[242:245], v[72:75]
	s_setprio 0
	s_setprio 1
	v_mfma_f32_16x16x32_bf16 v[116:119], v[180:183], v[214:217], v[116:119]
	v_mfma_f32_16x16x32_bf16 v[108:111], v[188:191], v[214:217], v[108:111]
	v_mfma_f32_16x16x32_bf16 v[100:103], v[180:183], v[222:225], v[100:103]
	v_mfma_f32_16x16x32_bf16 v[92:95], v[188:191], v[222:225], v[92:95]
	v_mfma_f32_16x16x32_bf16 v[84:87], v[180:183], v[230:233], v[84:87]
	v_mfma_f32_16x16x32_bf16 v[76:79], v[188:191], v[230:233], v[76:79]
	v_mfma_f32_16x16x32_bf16 v[68:71], v[180:183], v[238:241], v[68:71]
	v_mfma_f32_16x16x32_bf16 v[64:67], v[188:191], v[238:241], v[64:67]
	v_mfma_f32_16x16x32_bf16 v[116:119], v[184:187], v[218:221], v[116:119]
	v_mfma_f32_16x16x32_bf16 v[108:111], v[210:213], v[218:221], v[108:111]
	v_mfma_f32_16x16x32_bf16 v[100:103], v[184:187], v[226:229], v[100:103]
	v_mfma_f32_16x16x32_bf16 v[92:95], v[210:213], v[226:229], v[92:95]
	v_mfma_f32_16x16x32_bf16 v[84:87], v[184:187], v[234:237], v[84:87]
	v_mfma_f32_16x16x32_bf16 v[76:79], v[210:213], v[234:237], v[76:79]
	s_barrier
; #define PG8_STAGE(bufoff, gbase, voff) do { _Pragma("unroll") for (int _i = 0; _i < 2; ++_i) \
;         __builtin_amdgcn_global_load_lds((const unsigned*)((const char*)(gbase) + (voff)[_i]), (PG8_LAS unsigned*)(lds + (bufoff) + ldsw + _i * 8192), 16, 0, 0); } while (0)
; #define PG8_LDA(dst, b, h) do { _Pragma("unroll") for (int m = 0; m < 4; ++m) _Pragma("unroll") for (int k = 0; k < 2; ++k) dst[m][k] = *(const PG8_LAS bf16x8*)(lds + PG8_SA(b, h) + aoff + m * 2048 + k * 1024); } while (0)
; #define PG8_MMA(ai, bj, At, Bt) do { __builtin_amdgcn_s_setprio(1); _Pragma("unroll") for (int m = 0; m < 4; ++m) _Pragma("unroll") for (int n = 0; n < 2; ++n) _Pragma("unroll") for (int k = 0; k < 2; ++k) \
;         acc[ai][bj][m][n] = __builtin_amdgcn_mfma_f32_16x16x32_bf16(Bt[n][k], At[m][k], acc[ai][bj][m][n], 0, 0, 0); __builtin_amdgcn_s_setprio(0); } while (0)
; #define PG8_WAIT_V(n) asm volatile("s_waitcnt vmcnt(" #n ")" ::: "memory")
; #define PG8_WAIT_L(n) asm volatile("s_waitcnt lgkmcnt(" #n ")" ::: "memory")
; #define PG8_BAR __builtin_amdgcn_s_barrier()
; #define PG8_SCHED __builtin_amdgcn_sched_barrier(0)
; template <class Epi, class Sched, bool ALIGN_EPI = false, bool SP2 = false>
; __device__ __forceinline__ void gemm_phase(PG8_LAS unsigned char* lds, const Gemm g, const Sched& S, const Epi& E) {
;     ...
;             PG8_WAIT_V(8); PG8_WAIT_L(0); PG8_BAR; PG8_MMA(0, 0, At, B0); PG8_MMA(0, 1, At, B1); PG8_BAR; PG8_SCHED;
;             PG8_LDA(At, 1, 1); PG8_STAGE(PG8_SB(1, 0), b3, voffB); PG8_STAGE(PG8_SB(1, 1), b3 + hstep, voffB); PG8_STAGE(PG8_SA(1, 0), a3, voffA);
;             PG8_WAIT_V(8); PG8_WAIT_L(0); PG8_BAR; PG8_MMA(1, 0, At, B0); PG8_MMA(1, 1, At, B1); PG8_BAR; PG8_SCHED;
	v_mfma_f32_16x16x32_bf16 v[68:71], v[184:187], v[242:245], v[68:71]
	v_mfma_f32_16x16x32_bf16 v[64:67], v[210:213], v[242:245], v[64:67]
	s_setprio 0
	s_mov_b32 m0, s37
	v_lshl_add_u64 v[170:171], v[170:171], 0, s[94:95]
	s_add_u32 s2, s2, 0x40080
	ds_read_b128 v[214:217], v173 offset:49152
	ds_read_b128 v[218:221], v173 offset:50176
	ds_read_b128 v[222:225], v173 offset:51200
	ds_read_b128 v[226:229], v173 offset:52224
	ds_read_b128 v[230:233], v173 offset:53248
	ds_read_b128 v[234:237], v173 offset:54272
	ds_read_b128 v[238:241], v173 offset:55296
	ds_read_b128 v[242:245], v173 offset:56320
	global_load_lds_dwordx4 v[170:171], off
	v_lshl_add_u64 v[170:171], v[208:209], 0, s[94:95]
	s_mov_b32 m0, s38
	s_addc_u32 s3, s3, 0
	global_load_lds_dwordx4 v[170:171], off
	v_lshl_add_u64 v[170:171], s[2:3], 0, v[132:133]
	s_mov_b32 m0, s41
	s_nop 0
	global_load_lds_dwordx4 v[170:171], off
	v_lshl_add_u64 v[170:171], s[2:3], 0, v[128:129]
	s_mov_b32 m0, s42
	s_nop 0
	global_load_lds_dwordx4 v[170:171], off
	v_lshl_add_u64 v[170:171], v[246:247], 0, s[94:95]
	s_mov_b32 m0, s39
	s_nop 0
	global_load_lds_dwordx4 v[170:171], off
	v_lshl_add_u64 v[170:171], v[248:249], 0, s[94:95]
	s_mov_b32 m0, s40
	s_nop 0
	global_load_lds_dwordx4 v[170:171], off
	s_waitcnt vmcnt(8)
	s_waitcnt lgkmcnt(0)
	s_barrier
	s_setprio 1
	s_waitcnt lgkmcnt(0)
	v_mfma_f32_16x16x32_bf16 v[60:63], v[140:143], v[214:217], v[60:63]
	v_mfma_f32_16x16x32_bf16 v[56:59], v[166:169], v[214:217], v[56:59]
	v_mfma_f32_16x16x32_bf16 v[48:51], v[140:143], v[222:225], v[48:51]
	v_mfma_f32_16x16x32_bf16 v[40:43], v[166:169], v[222:225], v[40:43]
	v_mfma_f32_16x16x32_bf16 v[32:35], v[140:143], v[230:233], v[32:35]
	v_mfma_f32_16x16x32_bf16 v[24:27], v[166:169], v[230:233], v[24:27]
	v_mfma_f32_16x16x32_bf16 v[16:19], v[140:143], v[238:241], v[16:19]
	v_mfma_f32_16x16x32_bf16 v[8:11], v[166:169], v[238:241], v[8:11]
	v_mfma_f32_16x16x32_bf16 v[60:63], v[162:165], v[218:221], v[60:63]
	v_mfma_f32_16x16x32_bf16 v[56:59], v[176:179], v[218:221], v[56:59]
	v_mfma_f32_16x16x32_bf16 v[48:51], v[162:165], v[226:229], v[48:51]
	v_mfma_f32_16x16x32_bf16 v[40:43], v[176:179], v[226:229], v[40:43]
	v_mfma_f32_16x16x32_bf16 v[32:35], v[162:165], v[234:237], v[32:35]
	v_mfma_f32_16x16x32_bf16 v[24:27], v[176:179], v[234:237], v[24:27]
	v_mfma_f32_16x16x32_bf16 v[16:19], v[162:165], v[242:245], v[16:19]
	v_mfma_f32_16x16x32_bf16 v[8:11], v[176:179], v[242:245], v[8:11]
	s_setprio 0
	s_setprio 1
	v_mfma_f32_16x16x32_bf16 v[52:55], v[180:183], v[214:217], v[52:55]
	v_mfma_f32_16x16x32_bf16 v[44:47], v[188:191], v[214:217], v[44:47]
	v_mfma_f32_16x16x32_bf16 v[36:39], v[180:183], v[222:225], v[36:39]
	v_mfma_f32_16x16x32_bf16 v[28:31], v[188:191], v[222:225], v[28:31]
	v_mfma_f32_16x16x32_bf16 v[20:23], v[180:183], v[230:233], v[20:23]
	v_mfma_f32_16x16x32_bf16 v[12:15], v[188:191], v[230:233], v[12:15]
	v_mfma_f32_16x16x32_bf16 v[4:7], v[180:183], v[238:241], v[4:7]
	v_mfma_f32_16x16x32_bf16 v[0:3], v[188:191], v[238:241], v[0:3]
	v_mfma_f32_16x16x32_bf16 v[52:55], v[184:187], v[218:221], v[52:55]
	v_mfma_f32_16x16x32_bf16 v[44:47], v[210:213], v[218:221], v[44:47]
	v_mfma_f32_16x16x32_bf16 v[36:39], v[184:187], v[226:229], v[36:39]
	v_mfma_f32_16x16x32_bf16 v[28:31], v[210:213], v[226:229], v[28:31]
	v_mfma_f32_16x16x32_bf16 v[20:23], v[184:187], v[234:237], v[20:23]
	v_mfma_f32_16x16x32_bf16 v[12:15], v[210:213], v[234:237], v[12:15]
	s_barrier
	v_mfma_f32_16x16x32_bf16 v[4:7], v[184:187], v[242:245], v[4:7]
	v_mfma_f32_16x16x32_bf16 v[0:3], v[210:213], v[242:245], v[0:3]
	s_setprio 0
	s_add_i32 s52, s52, 2
	s_add_u32 s0, s0, 0x100
	s_addc_u32 s1, s1, 0
	s_add_u32 s50, s50, 0x100
	s_addc_u32 s51, s51, 0
	s_cmp_gt_u32 s52, 13
	s_cbranch_scc0 .LBB0_792
	s_and_b64 vcc, exec, s[12:13]
	s_cbranch_vccz .LBB0_795
	s_barrier

; #define PG8_STAGE(bufoff, gbase, voff) do { _Pragma("unroll") for (int _i = 0; _i < 2; ++_i) \
;         __builtin_amdgcn_global_load_lds((const unsigned*)((const char*)(gbase) + (voff)[_i]), (PG8_LAS unsigned*)(lds + (bufoff) + ldsw + _i * 8192), 16, 0, 0); } while (0)
; #define PG8_LDA(dst, b, h) do { _Pragma("unroll") for (int m = 0; m < 4; ++m) _Pragma("unroll") for (int k = 0; k < 2; ++k) dst[m][k] = *(const PG8_LAS bf16x8*)(lds + PG8_SA(b, h) + aoff + m * 2048 + k * 1024); } while (0)
; #define PG8_LDB(dst, b, h) do { _Pragma("unroll") for (int n = 0; n < 2; ++n) _Pragma("unroll") for (int k = 0; k < 2; ++k) dst[n][k] = *(const PG8_LAS bf16x8*)(lds + PG8_SB(b, h) + boff + n * 2048 + k * 1024); } while (0)
; #define PG8_MMA(ai, bj, At, Bt) do { __builtin_amdgcn_s_setprio(1); _Pragma("unroll") for (int m = 0; m < 4; ++m) _Pragma("unroll") for (int n = 0; n < 2; ++n) _Pragma("unroll") for (int k = 0; k < 2; ++k) \
;         acc[ai][bj][m][n] = __builtin_amdgcn_mfma_f32_16x16x32_bf16(Bt[n][k], At[m][k], acc[ai][bj][m][n], 0, 0, 0); __builtin_amdgcn_s_setprio(0); } while (0)
; #define PG8_WAIT_V(n) asm volatile("s_waitcnt vmcnt(" #n ")" ::: "memory")
; #define PG8_WAIT_L(n) asm volatile("s_waitcnt lgkmcnt(" #n ")" ::: "memory")
; #define PG8_BAR __builtin_amdgcn_s_barrier()
; #define PG8_SCHED __builtin_amdgcn_sched_barrier(0)
; template <class Epi, class Sched, bool ALIGN_EPI = false, bool SP2 = false>
; __device__ __forceinline__ void gemm_phase(PG8_LAS unsigned char* lds, const Gemm g, const Sched& S, const Epi& E) {
;     ...
;             const bool last = (t == nt - 2);
;             const char* a1 = cA + (size_t)(t + 1) * kstep;
;             const char* a2 = last ? nA : cA + (size_t)(t + 2) * kstep; const char* b2 = last ? nB : cB + (size_t)(t + 2) * kstep;
;             const char* a3 = a2 + kstep; const char* b3 = b2 + kstep;
;             if (last && has_next) S.a_ready(nxt);
;             if constexpr (SP2) {
;             PG8_LDB(B0, 0, 0); PG8_LDB(B1, 0, 1); PG8_SCHED; PG8_LDA(At, 0, 0); PG8_STAGE(PG8_SA(1, 1), a1 + hstep, voffA);
;             PG8_WAIT_V(8); PG8_WAIT_L(0); PG8_BAR; PG8_MMA(0, 0, At, B0); PG8_MMA(0, 1, At, B1); PG8_BAR; PG8_SCHED;
;             PG8_LDA(At, 0, 1); PG8_STAGE(PG8_SB(0, 0), b2, voffB); PG8_STAGE(PG8_SB(0, 1), b2 + hstep, voffB); PG8_STAGE(PG8_SA(0, 0), a2, voffA);
.LBB0_1042:
	v_or_b32_e32 v140, 0x10000, v164
	v_add_u32_e32 v165, 0x10400, v164
	ds_read_b128 v[140:143], v140
	ds_read_b128 v[166:169], v165
	v_add_u32_e32 v165, 0x10800, v164
	v_add_u32_e32 v174, 0x10c00, v164
	ds_read_b128 v[170:173], v165
	ds_read_b128 v[174:177], v174
	v_or_b32_e32 v165, 0x14000, v164
	v_add_u32_e32 v182, 0x14400, v164
	ds_read_b128 v[178:181], v165
	ds_read_b128 v[182:185], v182
	v_add_u32_e32 v165, 0x14800, v164
	v_add_u32_e32 v190, 0x14c00, v164
	ds_read_b128 v[186:189], v165
	ds_read_b128 v[210:213], v190
	s_add_u32 s2, s0, 0xfffc0080
	s_addc_u32 s3, s1, -1
	s_cmp_eq_u32 s55, 12
	s_cselect_b32 s5, s23, s3
	s_cselect_b32 s4, s51, s2
	s_cselect_b32 s3, s21, s54
	s_cselect_b32 s2, s52, s53
	v_lshl_add_u64 v[190:191], s[0:1], 0, v[136:137]
	s_add_i32 m0, s31, 0xc000
	ds_read_b128 v[214:217], v163
	ds_read_b128 v[218:221], v163 offset:1024
	ds_read_b128 v[222:225], v163 offset:2048
	ds_read_b128 v[226:229], v163 offset:3072
	ds_read_b128 v[230:233], v163 offset:4096
	ds_read_b128 v[234:237], v163 offset:5120
	ds_read_b128 v[238:241], v163 offset:6144
	ds_read_b128 v[242:245], v163 offset:7168
	global_load_lds_dwordx4 v[190:191], off
	v_lshl_add_u64 v[190:191], s[0:1], 0, v[138:139]
	s_add_i32 m0, s31, 0xe000
	s_nop 0
	global_load_lds_dwordx4 v[190:191], off
	s_waitcnt vmcnt(8)
	s_waitcnt lgkmcnt(0)
	s_barrier
	s_setprio 1
	s_waitcnt lgkmcnt(0)
	v_mfma_f32_16x16x32_bf16 v[124:127], v[140:143], v[214:217], v[124:127]
	v_mfma_f32_16x16x32_bf16 v[120:123], v[170:173], v[214:217], v[120:123]
	v_mfma_f32_16x16x32_bf16 v[108:111], v[140:143], v[222:225], v[108:111]
	v_mfma_f32_16x16x32_bf16 v[104:107], v[170:173], v[222:225], v[104:107]
	v_mfma_f32_16x16x32_bf16 v[92:95], v[140:143], v[230:233], v[92:95]
	v_mfma_f32_16x16x32_bf16 v[88:91], v[170:173], v[230:233], v[88:91]
	v_mfma_f32_16x16x32_bf16 v[76:79], v[140:143], v[238:241], v[76:79]
	v_mfma_f32_16x16x32_bf16 v[72:75], v[170:173], v[238:241], v[72:75]
	v_mfma_f32_16x16x32_bf16 v[124:127], v[166:169], v[218:221], v[124:127]
	v_mfma_f32_16x16x32_bf16 v[120:123], v[174:177], v[218:221], v[120:123]
	v_mfma_f32_16x16x32_bf16 v[108:111], v[166:169], v[226:229], v[108:111]
	v_mfma_f32_16x16x32_bf16 v[104:107], v[174:177], v[226:229], v[104:107]
	v_mfma_f32_16x16x32_bf16 v[92:95], v[166:169], v[234:237], v[92:95]
	v_mfma_f32_16x16x32_bf16 v[88:91], v[174:177], v[234:237], v[88:91]
	v_mfma_f32_16x16x32_bf16 v[76:79], v[166:169], v[242:245], v[76:79]
	v_mfma_f32_16x16x32_bf16 v[72:75], v[174:177], v[242:245], v[72:75]
	s_setprio 0
	s_setprio 1
	v_mfma_f32_16x16x32_bf16 v[116:119], v[178:181], v[214:217], v[116:119]
	v_mfma_f32_16x16x32_bf16 v[112:115], v[186:189], v[214:217], v[112:115]
	v_mfma_f32_16x16x32_bf16 v[100:103], v[178:181], v[222:225], v[100:103]
	v_mfma_f32_16x16x32_bf16 v[96:99], v[186:189], v[222:225], v[96:99]
	v_mfma_f32_16x16x32_bf16 v[84:87], v[178:181], v[230:233], v[84:87]
	v_mfma_f32_16x16x32_bf16 v[80:83], v[186:189], v[230:233], v[80:83]
	v_mfma_f32_16x16x32_bf16 v[68:71], v[178:181], v[238:241], v[68:71]
	v_mfma_f32_16x16x32_bf16 v[64:67], v[186:189], v[238:241], v[64:67]
	v_mfma_f32_16x16x32_bf16 v[116:119], v[182:185], v[218:221], v[116:119]
	v_mfma_f32_16x16x32_bf16 v[112:115], v[210:213], v[218:221], v[112:115]
	v_mfma_f32_16x16x32_bf16 v[100:103], v[182:185], v[226:229], v[100:103]
	v_mfma_f32_16x16x32_bf16 v[96:99], v[210:213], v[226:229], v[96:99]
	v_mfma_f32_16x16x32_bf16 v[84:87], v[182:185], v[234:237], v[84:87]
	v_mfma_f32_16x16x32_bf16 v[80:83], v[210:213], v[234:237], v[80:83]
	s_barrier
	v_mfma_f32_16x16x32_bf16 v[68:71], v[182:185], v[242:245], v[68:71]
	v_mfma_f32_16x16x32_bf16 v[64:67], v[210:213], v[242:245], v[64:67]
	s_setprio 0
	s_mov_b32 m0, s33
	v_lshl_add_u64 v[190:191], s[2:3], 0, v[132:133]
	s_add_u32 s56, s2, 0x40000
	ds_read_b128 v[214:217], v163 offset:16384
	ds_read_b128 v[218:221], v163 offset:17408
	ds_read_b128 v[222:225], v163 offset:18432
	ds_read_b128 v[226:229], v163 offset:19456
	ds_read_b128 v[230:233], v163 offset:20480
	ds_read_b128 v[234:237], v163 offset:21504
	ds_read_b128 v[238:241], v163 offset:22528
	ds_read_b128 v[242:245], v163 offset:23552
	global_load_lds_dwordx4 v[190:191], off
	v_lshl_add_u64 v[208:209], s[2:3], 0, v[128:129]
	s_mov_b32 m0, s34
	s_addc_u32 s57, s3, 0
	global_load_lds_dwordx4 v[208:209], off
	v_lshl_add_u64 v[246:247], s[56:57], 0, v[132:133]
	s_mov_b32 m0, s35
	v_lshl_add_u64 v[248:249], s[4:5], 0, v[130:131]
	global_load_lds_dwordx4 v[246:247], off
	v_lshl_add_u64 v[246:247], s[56:57], 0, v[128:129]
	s_mov_b32 m0, s36
	s_nop 0
	global_load_lds_dwordx4 v[246:247], off
	v_lshl_add_u64 v[246:247], s[4:5], 0, v[134:135]
	s_mov_b32 m0, s31
	s_nop 0
	global_load_lds_dwordx4 v[246:247], off
	s_mov_b32 m0, s37
	s_nop 0
	global_load_lds_dwordx4 v[248:249], off
	s_waitcnt vmcnt(8)
	s_waitcnt lgkmcnt(0)
	s_barrier
; #define PG8_STAGE(bufoff, gbase, voff) do { _Pragma("unroll") for (int _i = 0; _i < 2; ++_i) \
;         __builtin_amdgcn_global_load_lds((const unsigned*)((const char*)(gbase) + (voff)[_i]), (PG8_LAS unsigned*)(lds + (bufoff) + ldsw + _i * 8192), 16, 0, 0); } while (0)
; #define PG8_LDA(dst, b, h) do { _Pragma("unroll") for (int m = 0; m < 4; ++m) _Pragma("unroll") for (int k = 0; k < 2; ++k) dst[m][k] = *(const PG8_LAS bf16x8*)(lds + PG8_SA(b, h) + aoff + m * 2048 + k * 1024); } while (0)
; #define PG8_LDB(dst, b, h) do { _Pragma("unroll") for (int n = 0; n < 2; ++n) _Pragma("unroll") for (int k = 0; k < 2; ++k) dst[n][k] = *(const PG8_LAS bf16x8*)(lds + PG8_SB(b, h) + boff + n * 2048 + k * 1024); } while (0)
; #define PG8_MMA(ai, bj, At, Bt) do { __builtin_amdgcn_s_setprio(1); _Pragma("unroll") for (int m = 0; m < 4; ++m) _Pragma("unroll") for (int n = 0; n < 2; ++n) _Pragma("unroll") for (int k = 0; k < 2; ++k) \
;         acc[ai][bj][m][n] = __builtin_amdgcn_mfma_f32_16x16x32_bf16(Bt[n][k], At[m][k], acc[ai][bj][m][n], 0, 0, 0); __builtin_amdgcn_s_setprio(0); } while (0)
; #define PG8_WAIT_V(n) asm volatile("s_waitcnt vmcnt(" #n ")" ::: "memory")
; #define PG8_WAIT_L(n) asm volatile("s_waitcnt lgkmcnt(" #n ")" ::: "memory")
; #define PG8_BAR __builtin_amdgcn_s_barrier()
; #define PG8_SCHED __builtin_amdgcn_sched_barrier(0)
; template <class Epi, class Sched, bool ALIGN_EPI = false, bool SP2 = false>
; __device__ __forceinline__ void gemm_phase(PG8_LAS unsigned char* lds, const Gemm g, const Sched& S, const Epi& E) {
;     ...
;             PG8_WAIT_V(8); PG8_WAIT_L(0); PG8_BAR; PG8_MMA(1, 0, At, B0); PG8_MMA(1, 1, At, B1); PG8_BAR; PG8_SCHED;
;             PG8_LDB(B0, 1, 0); PG8_LDB(B1, 1, 1); PG8_SCHED; PG8_LDA(At, 1, 0); PG8_STAGE(PG8_SA(0, 1), a2 + hstep, voffA);
;             PG8_WAIT_V(8); PG8_WAIT_L(0); PG8_BAR; PG8_MMA(0, 0, At, B0); PG8_MMA(0, 1, At, B1); PG8_BAR; PG8_SCHED;
	s_setprio 1
	s_waitcnt lgkmcnt(0)
	v_mfma_f32_16x16x32_bf16 v[60:63], v[140:143], v[214:217], v[60:63]
	v_mfma_f32_16x16x32_bf16 v[56:59], v[170:173], v[214:217], v[56:59]
	v_mfma_f32_16x16x32_bf16 v[44:47], v[140:143], v[222:225], v[44:47]
	v_mfma_f32_16x16x32_bf16 v[40:43], v[170:173], v[222:225], v[40:43]
	v_mfma_f32_16x16x32_bf16 v[28:31], v[140:143], v[230:233], v[28:31]
	v_mfma_f32_16x16x32_bf16 v[24:27], v[170:173], v[230:233], v[24:27]
	v_mfma_f32_16x16x32_bf16 v[12:15], v[140:143], v[238:241], v[12:15]
	v_mfma_f32_16x16x32_bf16 v[8:11], v[170:173], v[238:241], v[8:11]
	v_mfma_f32_16x16x32_bf16 v[60:63], v[166:169], v[218:221], v[60:63]
	v_mfma_f32_16x16x32_bf16 v[56:59], v[174:177], v[218:221], v[56:59]
	v_mfma_f32_16x16x32_bf16 v[44:47], v[166:169], v[226:229], v[44:47]
	v_mfma_f32_16x16x32_bf16 v[40:43], v[174:177], v[226:229], v[40:43]
	v_mfma_f32_16x16x32_bf16 v[28:31], v[166:169], v[234:237], v[28:31]
	v_mfma_f32_16x16x32_bf16 v[24:27], v[174:177], v[234:237], v[24:27]
	v_mfma_f32_16x16x32_bf16 v[12:15], v[166:169], v[242:245], v[12:15]
	v_mfma_f32_16x16x32_bf16 v[8:11], v[174:177], v[242:245], v[8:11]
	s_setprio 0
	s_setprio 1
	v_mfma_f32_16x16x32_bf16 v[52:55], v[178:181], v[214:217], v[52:55]
	v_mfma_f32_16x16x32_bf16 v[48:51], v[186:189], v[214:217], v[48:51]
	v_mfma_f32_16x16x32_bf16 v[36:39], v[178:181], v[222:225], v[36:39]
	v_mfma_f32_16x16x32_bf16 v[32:35], v[186:189], v[222:225], v[32:35]
	v_mfma_f32_16x16x32_bf16 v[20:23], v[178:181], v[230:233], v[20:23]
	v_mfma_f32_16x16x32_bf16 v[16:19], v[186:189], v[230:233], v[16:19]
	v_mfma_f32_16x16x32_bf16 v[4:7], v[178:181], v[238:241], v[4:7]
	v_mfma_f32_16x16x32_bf16 v[0:3], v[186:189], v[238:241], v[0:3]
	v_mfma_f32_16x16x32_bf16 v[52:55], v[182:185], v[218:221], v[52:55]
	v_mfma_f32_16x16x32_bf16 v[48:51], v[210:213], v[218:221], v[48:51]
	v_mfma_f32_16x16x32_bf16 v[36:39], v[182:185], v[226:229], v[36:39]
	v_mfma_f32_16x16x32_bf16 v[32:35], v[210:213], v[226:229], v[32:35]
	v_mfma_f32_16x16x32_bf16 v[20:23], v[182:185], v[234:237], v[20:23]
	v_mfma_f32_16x16x32_bf16 v[16:19], v[210:213], v[234:237], v[16:19]
	s_barrier
	v_mfma_f32_16x16x32_bf16 v[4:7], v[182:185], v[242:245], v[4:7]
	v_mfma_f32_16x16x32_bf16 v[0:3], v[210:213], v[242:245], v[0:3]
	s_setprio 0
	v_or_b32_e32 v140, 0x18000, v164
	v_add_u32_e32 v165, 0x18400, v164
	ds_read_b128 v[140:143], v140
	ds_read_b128 v[166:169], v165
	v_add_u32_e32 v165, 0x18800, v164
	v_add_u32_e32 v174, 0x18c00, v164
	ds_read_b128 v[170:173], v165
	ds_read_b128 v[174:177], v174
	v_or_b32_e32 v165, 0x1c000, v164
	v_add_u32_e32 v182, 0x1c400, v164
	ds_read_b128 v[178:181], v165
	ds_read_b128 v[182:185], v182
	v_add_u32_e32 v165, 0x1c800, v164
	v_add_u32_e32 v210, 0x1cc00, v164
	ds_read_b128 v[186:189], v165
	ds_read_b128 v[210:213], v210
	s_add_u32 s4, s4, 0x40000
	s_addc_u32 s5, s5, 0
	s_mov_b32 m0, s38
	v_lshl_add_u64 v[250:251], s[4:5], 0, v[134:135]
	ds_read_b128 v[214:217], v163 offset:32768
	ds_read_b128 v[218:221], v163 offset:33792
	ds_read_b128 v[222:225], v163 offset:34816
	ds_read_b128 v[226:229], v163 offset:35840
	ds_read_b128 v[230:233], v163 offset:36864
	ds_read_b128 v[234:237], v163 offset:37888
	ds_read_b128 v[238:241], v163 offset:38912
	ds_read_b128 v[242:245], v163 offset:39936
	global_load_lds_dwordx4 v[250:251], off
	v_lshl_add_u64 v[250:251], s[4:5], 0, v[130:131]
	s_mov_b32 m0, s39
	s_nop 0
	global_load_lds_dwordx4 v[250:251], off
	s_waitcnt vmcnt(8)
	s_waitcnt lgkmcnt(0)
	s_barrier
	s_setprio 1
	s_waitcnt lgkmcnt(0)
	v_mfma_f32_16x16x32_bf16 v[124:127], v[140:143], v[214:217], v[124:127]
	v_mfma_f32_16x16x32_bf16 v[120:123], v[170:173], v[214:217], v[120:123]
	v_mfma_f32_16x16x32_bf16 v[108:111], v[140:143], v[222:225], v[108:111]
	v_mfma_f32_16x16x32_bf16 v[104:107], v[170:173], v[222:225], v[104:107]
	v_mfma_f32_16x16x32_bf16 v[92:95], v[140:143], v[230:233], v[92:95]
	v_mfma_f32_16x16x32_bf16 v[88:91], v[170:173], v[230:233], v[88:91]
	v_mfma_f32_16x16x32_bf16 v[76:79], v[140:143], v[238:241], v[76:79]
	v_mfma_f32_16x16x32_bf16 v[72:75], v[170:173], v[238:241], v[72:75]
	v_mfma_f32_16x16x32_bf16 v[124:127], v[166:169], v[218:221], v[124:127]
	v_mfma_f32_16x16x32_bf16 v[120:123], v[174:177], v[218:221], v[120:123]
	v_mfma_f32_16x16x32_bf16 v[108:111], v[166:169], v[226:229], v[108:111]
	v_mfma_f32_16x16x32_bf16 v[104:107], v[174:177], v[226:229], v[104:107]
	v_mfma_f32_16x16x32_bf16 v[92:95], v[166:169], v[234:237], v[92:95]
	v_mfma_f32_16x16x32_bf16 v[88:91], v[174:177], v[234:237], v[88:91]
	v_mfma_f32_16x16x32_bf16 v[76:79], v[166:169], v[242:245], v[76:79]
	v_mfma_f32_16x16x32_bf16 v[72:75], v[174:177], v[242:245], v[72:75]
	s_setprio 0
	s_setprio 1
	v_mfma_f32_16x16x32_bf16 v[116:119], v[178:181], v[214:217], v[116:119]
	v_mfma_f32_16x16x32_bf16 v[112:115], v[186:189], v[214:217], v[112:115]
	v_mfma_f32_16x16x32_bf16 v[100:103], v[178:181], v[222:225], v[100:103]
	v_mfma_f32_16x16x32_bf16 v[96:99], v[186:189], v[222:225], v[96:99]
	v_mfma_f32_16x16x32_bf16 v[84:87], v[178:181], v[230:233], v[84:87]
	v_mfma_f32_16x16x32_bf16 v[80:83], v[186:189], v[230:233], v[80:83]
	v_mfma_f32_16x16x32_bf16 v[68:71], v[178:181], v[238:241], v[68:71]
	v_mfma_f32_16x16x32_bf16 v[64:67], v[186:189], v[238:241], v[64:67]
	v_mfma_f32_16x16x32_bf16 v[116:119], v[182:185], v[218:221], v[116:119]
	v_mfma_f32_16x16x32_bf16 v[112:115], v[210:213], v[218:221], v[112:115]
	v_mfma_f32_16x16x32_bf16 v[100:103], v[182:185], v[226:229], v[100:103]
	v_mfma_f32_16x16x32_bf16 v[96:99], v[210:213], v[226:229], v[96:99]
	v_mfma_f32_16x16x32_bf16 v[84:87], v[182:185], v[234:237], v[84:87]
	v_mfma_f32_16x16x32_bf16 v[80:83], v[210:213], v[234:237], v[80:83]
	s_barrier
; #define PG8_STAGE(bufoff, gbase, voff) do { _Pragma("unroll") for (int _i = 0; _i < 2; ++_i) \
;         __builtin_amdgcn_global_load_lds((const unsigned*)((const char*)(gbase) + (voff)[_i]), (PG8_LAS unsigned*)(lds + (bufoff) + ldsw + _i * 8192), 16, 0, 0); } while (0)
; #define PG8_LDA(dst, b, h) do { _Pragma("unroll") for (int m = 0; m < 4; ++m) _Pragma("unroll") for (int k = 0; k < 2; ++k) dst[m][k] = *(const PG8_LAS bf16x8*)(lds + PG8_SA(b, h) + aoff + m * 2048 + k * 1024); } while (0)
; #define PG8_MMA(ai, bj, At, Bt) do { __builtin_amdgcn_s_setprio(1); _Pragma("unroll") for (int m = 0; m < 4; ++m) _Pragma("unroll") for (int n = 0; n < 2; ++n) _Pragma("unroll") for (int k = 0; k < 2; ++k) \
;         acc[ai][bj][m][n] = __builtin_amdgcn_mfma_f32_16x16x32_bf16(Bt[n][k], At[m][k], acc[ai][bj][m][n], 0, 0, 0); __builtin_amdgcn_s_setprio(0); } while (0)
; #define PG8_WAIT_V(n) asm volatile("s_waitcnt vmcnt(" #n ")" ::: "memory")
; #define PG8_WAIT_L(n) asm volatile("s_waitcnt lgkmcnt(" #n ")" ::: "memory")
; #define PG8_BAR __builtin_amdgcn_s_barrier()
; #define PG8_SCHED __builtin_amdgcn_sched_barrier(0)
; template <class Epi, class Sched, bool ALIGN_EPI = false, bool SP2 = false>
; __device__ __forceinline__ void gemm_phase(PG8_LAS unsigned char* lds, const Gemm g, const Sched& S, const Epi& E) {
;     ...
;             PG8_WAIT_V(8); PG8_WAIT_L(0); PG8_BAR; PG8_MMA(0, 0, At, B0); PG8_MMA(0, 1, At, B1); PG8_BAR; PG8_SCHED;
;             PG8_LDA(At, 1, 1); PG8_STAGE(PG8_SB(1, 0), b3, voffB); PG8_STAGE(PG8_SB(1, 1), b3 + hstep, voffB); PG8_STAGE(PG8_SA(1, 0), a3, voffA);
;             PG8_WAIT_V(8); PG8_WAIT_L(0); PG8_BAR; PG8_MMA(1, 0, At, B0); PG8_MMA(1, 1, At, B1); PG8_BAR; PG8_SCHED;
	v_mfma_f32_16x16x32_bf16 v[68:71], v[182:185], v[242:245], v[68:71]
	v_mfma_f32_16x16x32_bf16 v[64:67], v[210:213], v[242:245], v[64:67]
	s_setprio 0
	s_mov_b32 m0, s43
	v_lshl_add_u64 v[190:191], v[190:191], 0, s[94:95]
	s_add_u32 s2, s2, 0x40080
	ds_read_b128 v[214:217], v163 offset:49152
	ds_read_b128 v[218:221], v163 offset:50176
	ds_read_b128 v[222:225], v163 offset:51200
	ds_read_b128 v[226:229], v163 offset:52224
	ds_read_b128 v[230:233], v163 offset:53248
	ds_read_b128 v[234:237], v163 offset:54272
	ds_read_b128 v[238:241], v163 offset:55296
	ds_read_b128 v[242:245], v163 offset:56320
	global_load_lds_dwordx4 v[190:191], off
	v_lshl_add_u64 v[190:191], v[208:209], 0, s[94:95]
	s_mov_b32 m0, s44
	s_addc_u32 s3, s3, 0
	global_load_lds_dwordx4 v[190:191], off
	v_lshl_add_u64 v[190:191], s[2:3], 0, v[132:133]
	s_mov_b32 m0, s48
	s_nop 0
	global_load_lds_dwordx4 v[190:191], off
	v_lshl_add_u64 v[190:191], s[2:3], 0, v[128:129]
	s_mov_b32 m0, s49
	s_nop 0
	global_load_lds_dwordx4 v[190:191], off
	v_lshl_add_u64 v[190:191], v[246:247], 0, s[94:95]
	s_mov_b32 m0, s45
	s_nop 0
	global_load_lds_dwordx4 v[190:191], off
	v_lshl_add_u64 v[190:191], v[248:249], 0, s[94:95]
	s_mov_b32 m0, s47
	s_nop 0
	global_load_lds_dwordx4 v[190:191], off
	s_waitcnt vmcnt(8)
	s_waitcnt lgkmcnt(0)
	s_barrier
	s_setprio 1
	s_waitcnt lgkmcnt(0)
	v_mfma_f32_16x16x32_bf16 v[60:63], v[140:143], v[214:217], v[60:63]
	v_mfma_f32_16x16x32_bf16 v[56:59], v[170:173], v[214:217], v[56:59]
	v_mfma_f32_16x16x32_bf16 v[44:47], v[140:143], v[222:225], v[44:47]
	v_mfma_f32_16x16x32_bf16 v[40:43], v[170:173], v[222:225], v[40:43]
	v_mfma_f32_16x16x32_bf16 v[28:31], v[140:143], v[230:233], v[28:31]
	v_mfma_f32_16x16x32_bf16 v[24:27], v[170:173], v[230:233], v[24:27]
	v_mfma_f32_16x16x32_bf16 v[12:15], v[140:143], v[238:241], v[12:15]
	v_mfma_f32_16x16x32_bf16 v[8:11], v[170:173], v[238:241], v[8:11]
	v_mfma_f32_16x16x32_bf16 v[60:63], v[166:169], v[218:221], v[60:63]
	v_mfma_f32_16x16x32_bf16 v[56:59], v[174:177], v[218:221], v[56:59]
	v_mfma_f32_16x16x32_bf16 v[44:47], v[166:169], v[226:229], v[44:47]
	v_mfma_f32_16x16x32_bf16 v[40:43], v[174:177], v[226:229], v[40:43]
	v_mfma_f32_16x16x32_bf16 v[28:31], v[166:169], v[234:237], v[28:31]
	v_mfma_f32_16x16x32_bf16 v[24:27], v[174:177], v[234:237], v[24:27]
	v_mfma_f32_16x16x32_bf16 v[12:15], v[166:169], v[242:245], v[12:15]
	v_mfma_f32_16x16x32_bf16 v[8:11], v[174:177], v[242:245], v[8:11]
	s_setprio 0
	s_setprio 1
	v_mfma_f32_16x16x32_bf16 v[52:55], v[178:181], v[214:217], v[52:55]
	v_mfma_f32_16x16x32_bf16 v[48:51], v[186:189], v[214:217], v[48:51]
	v_mfma_f32_16x16x32_bf16 v[36:39], v[178:181], v[222:225], v[36:39]
	v_mfma_f32_16x16x32_bf16 v[32:35], v[186:189], v[222:225], v[32:35]
	v_mfma_f32_16x16x32_bf16 v[20:23], v[178:181], v[230:233], v[20:23]
	v_mfma_f32_16x16x32_bf16 v[16:19], v[186:189], v[230:233], v[16:19]
	v_mfma_f32_16x16x32_bf16 v[4:7], v[178:181], v[238:241], v[4:7]
	v_mfma_f32_16x16x32_bf16 v[0:3], v[186:189], v[238:241], v[0:3]
	v_mfma_f32_16x16x32_bf16 v[52:55], v[182:185], v[218:221], v[52:55]
	v_mfma_f32_16x16x32_bf16 v[48:51], v[210:213], v[218:221], v[48:51]
	v_mfma_f32_16x16x32_bf16 v[36:39], v[182:185], v[226:229], v[36:39]
	v_mfma_f32_16x16x32_bf16 v[32:35], v[210:213], v[226:229], v[32:35]
	v_mfma_f32_16x16x32_bf16 v[20:23], v[182:185], v[234:237], v[20:23]
	v_mfma_f32_16x16x32_bf16 v[16:19], v[210:213], v[234:237], v[16:19]
	s_barrier
	v_mfma_f32_16x16x32_bf16 v[4:7], v[182:185], v[242:245], v[4:7]
	v_mfma_f32_16x16x32_bf16 v[0:3], v[210:213], v[242:245], v[0:3]
	s_setprio 0
	s_add_i32 s55, s55, 2
	s_add_u32 s0, s0, 0x100
	s_addc_u32 s1, s1, 0
	s_add_u32 s53, s53, 0x100
	s_addc_u32 s54, s54, 0
	s_cmp_gt_u32 s55, 13
	s_cbranch_scc0 .LBB0_1042
	s_and_b64 vcc, exec, s[18:19]
	s_cbranch_vccz .LBB0_1045
	s_barrier
